# g3 (GLA chunk units): state / v / gr loads (96 KB per unit) issued after the alpha-weight loads so they fly during gla_cb instead of in the initial burst; on top of v22
# baseline (speedup 1.0000x reference)
.LBB0_846:
	s_ashr_i32 s0, s20, 8
	s_and_b32 s13, s20, 63
	s_bfe_u32 s12, s20, 0x20006
	s_add_i32 s13, s13, 1
	s_lshl_b32 s1, s0, 2
	s_or_b32 s26, s1, s12
	s_mul_hi_i32 s1, s0, 0x2080
	s_mul_i32 s21, s0, 0x2080
	s_lshl_b32 s0, s13, 7
	v_mov_b32_e32 v63, v136
	s_add_u32 s38, s21, s0
	s_addc_u32 s39, s1, 0
	v_ashrrev_i32_e32 v18, 6, v63
	s_lshl_b32 s1, s12, 6
	s_lshl_b32 s21, s12, 7
	v_and_b32_e32 v65, 63, v63
	v_lshlrev_b32_e32 v16, 4, v18
	s_add_u32 s34, s6, s21
	v_ashrrev_i32_e32 v17, 31, v16
	s_addc_u32 s35, s7, 0
	v_lshlrev_b32_e32 v138, 1, v65
	v_lshl_add_u64 v[28:29], s[38:39], 0, v[16:17]
	v_lshl_add_u64 v[0:1], s[34:35], 0, v[138:139]
	v_mad_u64_u32 v[0:1], s[34:35], v28, s22, v[0:1]
	s_movk_i32 s19, 0x3000
	v_mad_i32_i24 v1, v29, s22, v1
	v_add_co_u32_e32 v2, vcc, s19, v0
	s_movk_i32 s34, 0x5000
	s_nop 0
	v_addc_co_u32_e32 v3, vcc, 0, v1, vcc
	global_load_ushort v112, v[0:1], off offset:3072
	global_load_ushort v111, v[0:1], off offset:3584
	global_load_ushort v110, v[2:3], off offset:1024
	global_load_ushort v109, v[2:3], off offset:1536
	v_add_co_u32_e32 v2, vcc, s34, v0
	s_mov_b32 s18, 0x8000
	s_nop 0
	v_addc_co_u32_e32 v3, vcc, 0, v1, vcc
	global_load_ushort v108, v[2:3], off offset:3072
	global_load_ushort v107, v[2:3], off offset:3584
	v_add_co_u32_e32 v2, vcc, s18, v0
	s_mov_b32 s18, 0xa000
	s_nop 0
	v_addc_co_u32_e32 v3, vcc, 0, v1, vcc
	global_load_ushort v104, v[2:3], off offset:1024
	global_load_ushort v103, v[2:3], off offset:1536
	v_add_co_u32_e32 v2, vcc, s18, v0
	s_mov_b32 s18, 0xd000
	s_nop 0
	v_addc_co_u32_e32 v3, vcc, 0, v1, vcc
	global_load_ushort v106, v[2:3], off offset:3072
	global_load_ushort v105, v[2:3], off offset:3584
	v_add_co_u32_e32 v2, vcc, s18, v0
	s_mov_b32 s18, 0xf000
	s_nop 0
	v_addc_co_u32_e32 v3, vcc, 0, v1, vcc
	global_load_ushort v102, v[2:3], off offset:1024
	global_load_ushort v101, v[2:3], off offset:1536
	v_add_co_u32_e32 v2, vcc, s18, v0
	s_mov_b32 s18, 0x12000
	s_nop 0
	v_addc_co_u32_e32 v3, vcc, 0, v1, vcc
	global_load_ushort v100, v[2:3], off offset:3072
	global_load_ushort v99, v[2:3], off offset:3584
	v_add_co_u32_e32 v2, vcc, s18, v0
	s_mov_b32 s18, 0x17000
	s_nop 0
	v_addc_co_u32_e32 v3, vcc, 0, v1, vcc
	global_load_ushort v96, v[2:3], off offset:1024
	global_load_ushort v95, v[2:3], off offset:1536
	v_add_co_u32_e32 v2, vcc, s88, v0
	s_mulk_i32 s26, 0x41
	s_nop 0
	v_addc_co_u32_e32 v3, vcc, 0, v1, vcc
	global_load_ushort v98, v[2:3], off offset:3072
	global_load_ushort v97, v[2:3], off offset:3584
	v_add_co_u32_e32 v2, vcc, s18, v0
	s_mov_b32 s18, 0x19000
	s_nop 0
	v_addc_co_u32_e32 v3, vcc, 0, v1, vcc
	global_load_ushort v94, v[2:3], off offset:1024
	global_load_ushort v93, v[2:3], off offset:1536
	v_add_co_u32_e32 v2, vcc, s18, v0
	s_mov_b32 s18, 0x1c000
	s_nop 0
	v_addc_co_u32_e32 v3, vcc, 0, v1, vcc
	global_load_ushort v89, v[2:3], off offset:3072
	global_load_ushort v88, v[2:3], off offset:3584
	v_add_co_u32_e32 v2, vcc, s18, v0
	s_mov_b32 s18, 0x1e000
	s_nop 0
	v_addc_co_u32_e32 v3, vcc, 0, v1, vcc
	global_load_ushort v77, v[2:3], off offset:1024
	global_load_ushort v76, v[2:3], off offset:1536
	v_add_co_u32_e32 v2, vcc, s18, v0
	s_mov_b32 s18, 0x21000
	s_nop 0
	v_addc_co_u32_e32 v3, vcc, 0, v1, vcc
	global_load_ushort v83, v[2:3], off offset:3072
	global_load_ushort v81, v[2:3], off offset:3584
	v_add_co_u32_e32 v2, vcc, s18, v0
	s_mov_b32 s18, 0x23000
	s_nop 0
	v_addc_co_u32_e32 v3, vcc, 0, v1, vcc
	global_load_ushort v75, v[2:3], off offset:1024
	global_load_ushort v74, v[2:3], off offset:1536
	v_add_co_u32_e32 v2, vcc, s18, v0
	s_mov_b32 s18, 0x26000
	s_nop 0
	v_addc_co_u32_e32 v3, vcc, 0, v1, vcc
	v_add_co_u32_e32 v0, vcc, s18, v0
	s_add_i32 s26, s26, s13
	s_nop 0
	v_addc_co_u32_e32 v1, vcc, 0, v1, vcc
	global_load_ushort v68, v[2:3], off offset:3072
	global_load_ushort v67, v[2:3], off offset:3584
	global_load_ushort v66, v[0:1], off offset:1024
	global_load_ushort v17, v[0:1], off offset:1536
	v_mov_b32_e32 v190, v28
	v_mov_b32_e32 v191, v29
	s_lshl_b32 s74, s12, 8
	v_mov_b32_e32 v25, v136
	s_lshl_b64 s[12:13], s[38:39], 6
	s_add_u32 s12, s78, s12
	s_addc_u32 s13, s79, s13
	v_lshlrev_b32_e32 v28, 2, v25
	v_ashrrev_i32_e32 v29, 31, v28
	v_lshl_add_u64 v[28:29], v[28:29], 2, s[12:13]
	global_load_dwordx4 v[28:31], v[28:29], off
	v_lshl_add_u32 v23, v25, 4, 0
	v_and_b32_e32 v21, 63, v25
	v_add_u32_e32 v23, 0x1e000, v23
	s_or_b32 s12, s1, s83
	v_readlane_b32 s40, v251, 8
	v_readlane_b32 s46, v251, 14
	v_readlane_b32 s47, v251, 15
	s_or_b32 s1, s1, s77
	v_readlane_b32 s48, v251, 16
	v_readlane_b32 s49, v251, 17
	s_waitcnt vmcnt(62)
	v_mov_b32_e32 v113, 0
	v_mov_b32_e32 v27, 0
	v_readlane_b32 s41, v251, 9
	v_readlane_b32 s42, v251, 10
	v_readlane_b32 s43, v251, 11
	v_readlane_b32 s44, v251, 12
	v_readlane_b32 s45, v251, 13
	v_readlane_b32 s50, v251, 18
	v_readlane_b32 s51, v251, 19
	v_readlane_b32 s52, v251, 20
	v_readlane_b32 s53, v251, 21
	v_readlane_b32 s54, v251, 22
	v_readlane_b32 s55, v251, 23
	s_waitcnt vmcnt(0)
	ds_write_b128 v23, v[28:31]
	v_or_b32_e32 v28, s12, v21
	v_mov_b32_e32 v29, v139
	v_lshl_add_u64 v[114:115], v[28:29], 2, s[46:47]
	v_add_co_u32_e32 v36, vcc, s97, v114
	global_load_dword v28, v[114:115], off
	global_load_dword v34, v[114:115], off offset:1024
	global_load_dword v30, v[114:115], off offset:2048
	global_load_dword v32, v[114:115], off offset:3072
	v_addc_co_u32_e32 v37, vcc, 0, v115, vcc
	v_add_co_u32_e32 v42, vcc, s8, v114
	v_ashrrev_i32_e32 v23, 6, v25
	s_nop 0
	v_addc_co_u32_e32 v43, vcc, 0, v115, vcc
	global_load_dword v29, v[42:43], off offset:-4096
	global_load_dword v35, v[36:37], off offset:1024
	global_load_dword v31, v[36:37], off offset:2048
	global_load_dword v33, v[36:37], off offset:3072
	s_nop 0
	global_load_dword v36, v[42:43], off
	global_load_dword v60, v[42:43], off offset:1024
	global_load_dword v38, v[42:43], off offset:2048
	s_nop 0
	global_load_dword v42, v[42:43], off offset:3072
	v_add_co_u32_e32 v114, vcc, s19, v114
	s_sub_i32 s12, 0x6f, s0
	s_nop 0
	v_addc_co_u32_e32 v115, vcc, 0, v115, vcc
	global_load_dword v37, v[114:115], off
	global_load_dword v61, v[114:115], off offset:1024
	global_load_dword v39, v[114:115], off offset:2048
	global_load_dword v43, v[114:115], off offset:3072
	v_or_b32_e32 v114, s1, v21
	v_mov_b32_e32 v115, v139
	v_lshl_add_u64 v[114:115], v[114:115], 2, s[48:49]
	global_load_dword v41, v[114:115], off
	s_ashr_i32 s27, s26, 31
	v_lshlrev_b32_e32 v0, 2, v65
	v_mov_b32_e32 v1, v139
	v_ashrrev_i32_e32 v19, 31, v18
	v_lshl_add_u64 v[0:1], s[4:5], 0, v[0:1]
	s_lshl_b64 s[26:27], s[26:27], 15
	v_lshlrev_b64 v[2:3], 8, v[18:19]
	v_lshl_add_u64 v[0:1], v[0:1], 0, s[26:27]
	v_lshl_add_u64 v[0:1], v[0:1], 0, v[2:3]
	v_add_co_u32_e32 v2, vcc, s97, v0
	global_load_dword v73, v[0:1], off
	global_load_dword v69, v[0:1], off offset:2048
	v_addc_co_u32_e32 v3, vcc, 0, v1, vcc
	v_add_co_u32_e32 v4, vcc, s8, v0
	s_movk_i32 s101, 0x4000
	s_nop 0
	v_addc_co_u32_e32 v5, vcc, 0, v1, vcc
	global_load_dword v72, v[4:5], off offset:-4096
	global_load_dword v71, v[2:3], off offset:2048
	global_load_dword v70, v[4:5], off
	global_load_dword v19, v[4:5], off offset:2048
	v_add_co_u32_e32 v2, vcc, s19, v0
	v_and_b32_e32 v90, 0x7f, v63
	s_nop 0
	v_addc_co_u32_e32 v3, vcc, 0, v1, vcc
	v_add_co_u32_e32 v4, vcc, s101, v0
	s_movk_i32 s101, 0x6000
	s_nop 0
	v_addc_co_u32_e32 v5, vcc, 0, v1, vcc
	global_load_dword v82, v[4:5], off offset:-4096
	global_load_dword v79, v[2:3], off offset:2048
	global_load_dword v80, v[4:5], off
	global_load_dword v78, v[4:5], off offset:2048
	v_add_co_u32_e32 v2, vcc, s34, v0
	v_mov_b64_e32 v[242:243], s[6:7]
	s_nop 0
	v_addc_co_u32_e32 v3, vcc, 0, v1, vcc
	v_add_co_u32_e32 v4, vcc, s101, v0
	s_movk_i32 s101, 0x7000
	s_nop 0
	v_addc_co_u32_e32 v5, vcc, 0, v1, vcc
	v_add_co_u32_e32 v0, vcc, s101, v0
	global_load_dword v87, v[4:5], off offset:-4096
	global_load_dword v85, v[2:3], off offset:2048
	global_load_dword v86, v[4:5], off
	global_load_dword v84, v[4:5], off offset:2048
	v_addc_co_u32_e32 v1, vcc, 0, v1, vcc
	global_load_dword v92, v[0:1], off
	global_load_dword v91, v[0:1], off offset:2048
	v_or_b32_e32 v0, s38, v90
	v_mad_u64_u32 v[0:1], s[26:27], v0, s22, v[242:243]
	v_mad_i32_i24 v1, s39, v184, v1
	v_lshl_add_u64 v[0:1], v[0:1], 0, s[74:75]
	s_mov_b64 s[100:101], 0x1000
	v_lshl_add_u64 v[12:13], v[0:1], 0, s[100:101]
	v_ashrrev_i32_e32 v0, 4, v63
	v_add_u32_e32 v4, 0x200, v63
	v_and_b32_e32 v232, -8, v0
	v_ashrrev_i32_e32 v4, 4, v4
	v_and_b32_e32 v62, 15, v63
	v_ashrrev_i32_e32 v233, 31, v232
	v_and_b32_e32 v234, -8, v4
	v_lshl_add_u64 v[0:1], v[232:233], 1, v[12:13]
	v_ashrrev_i32_e32 v235, 31, v234
	v_or_b32_e32 v233, v190, v62
	v_lshl_add_u64 v[4:5], v[234:235], 1, v[12:13]
	v_mad_u64_u32 v[242:243], s[100:101], v233, s22, v[242:243]
	v_bfe_u32 v64, v63, 4, 2
	global_load_dwordx4 v[0:3], v[0:1], off
	v_add_u32_e32 v14, 0x600, v63
	global_load_dwordx4 v[8:11], v[4:5], off
	v_add_u32_e32 v4, 0x400, v63
	v_mad_i32_i24 v243, v191, s22, v243
	v_ashrrev_i32_e32 v4, 4, v4
	v_ashrrev_i32_e32 v14, 4, v14
	v_lshl_add_u64 v[240:241], v[242:243], 0, s[74:75]
	v_lshlrev_b32_e32 v244, 3, v64
	v_mov_b32_e32 v245, v139
	v_and_b32_e32 v236, -8, v4
	v_and_b32_e32 v238, -8, v14
	v_lshl_add_u64 v[240:241], v[240:241], 0, v[244:245]
	v_ashrrev_i32_e32 v237, 31, v236
	v_ashrrev_i32_e32 v239, 31, v238
	v_lshl_add_u64 v[242:243], v[240:241], 0, s[36:37]
	v_add_co_u32_e32 v240, vcc, s97, v240
	v_lshl_add_u64 v[4:5], v[236:237], 1, v[12:13]
	v_lshl_add_u64 v[12:13], v[238:239], 1, v[12:13]
	v_addc_co_u32_e32 v241, vcc, 0, v241, vcc
	global_load_dwordx4 v[4:7], v[4:5], off
	global_load_dwordx4 v[12:15], v[12:13], off
	s_nop 0
	global_load_dwordx2 v[58:59], v[240:241], off offset:1024
	global_load_dwordx2 v[56:57], v[242:243], off offset:32
	global_load_dwordx2 v[54:55], v[242:243], off offset:64
	global_load_dwordx2 v[52:53], v[242:243], off offset:96
	global_load_dwordx2 v[50:51], v[242:243], off offset:128
	global_load_dwordx2 v[48:49], v[242:243], off offset:160
	global_load_dwordx2 v[46:47], v[242:243], off offset:192
	global_load_dwordx2 v[44:45], v[242:243], off offset:224
	v_mov_b32_e32 v20, v232
	v_mov_b32_e32 v22, v234
	v_mov_b32_e32 v24, v236
	v_mov_b32_e32 v26, v238
	v_mov_b32_e32 v40, v244
	v_lshlrev_b32_e32 v114, 4, v23
	v_cmp_lt_i32_e32 vcc, s12, v114
	s_waitcnt lgkmcnt(0)
	s_barrier
	s_and_saveexec_b64 s[0:1], vcc
	s_cbranch_execz .LBB0_848
	v_lshl_add_u32 v27, v23, 10, 0
	v_add_u32_e32 v27, 0x1e000, v27
	ds_read_b128 v[116:119], v27
	ds_read_b128 v[120:123], v27 offset:16
	ds_read_b128 v[124:127], v27 offset:32
	ds_read_b128 v[128:131], v27 offset:48
	s_mov_b32 s13, 0x3d800000
	s_waitcnt lgkmcnt(3)
	v_mov_b32_e32 v132, v119
	s_waitcnt lgkmcnt(2)
	v_mov_b32_e32 v133, v123
	v_mov_b32_e32 v123, v120
	v_mov_b32_e32 v120, v117
	v_mov_b32_e32 v119, v122
	v_mov_b32_e32 v122, v116
	s_waitcnt vmcnt(39)
	v_pk_mul_f32 v[116:117], v[34:35], v[120:121]
	s_nop 0
	v_pk_fma_f32 v[116:117], v[28:29], v[122:123], v[116:117]
	s_waitcnt vmcnt(38)
	v_pk_fma_f32 v[116:117], v[30:31], v[118:119], v[116:117]
	s_waitcnt lgkmcnt(0)
	v_mov_b32_e32 v119, v128
	v_mov_b32_e32 v128, v125
	s_waitcnt vmcnt(37)
	v_pk_fma_f32 v[116:117], v[32:33], v[132:133], v[116:117]
	v_mov_b32_e32 v118, v124
	s_waitcnt vmcnt(31)
	v_pk_mul_f32 v[120:121], v[60:61], v[128:129]
	s_waitcnt vmcnt(28)
	v_add_f32_e32 v27, v41, v116
	v_mov_b32_e32 v116, v127
	v_mov_b32_e32 v127, v130
	v_pk_fma_f32 v[118:119], v[36:37], v[118:119], v[120:121]
	v_add_f32_e32 v27, v27, v117
	v_mov_b32_e32 v117, v131
	v_pk_fma_f32 v[118:119], v[38:39], v[126:127], v[118:119]
	s_nop 0
	v_pk_fma_f32 v[116:117], v[42:43], v[116:117], v[118:119]
	s_nop 0
	v_add_f32_e32 v27, v27, v116
	v_add_f32_e32 v27, v27, v117
	v_mul_f32_e64 v115, |v27|, s31
	v_exp_f32_e32 v115, v115
	v_min_f32_e32 v27, 0, v27
	v_add_f32_e32 v115, 1.0, v115
	v_cmp_gt_f32_e32 vcc, s28, v115
	s_nop 1
	v_cndmask_b32_e64 v116, 0, 32, vcc
	v_ldexp_f32 v115, v115, v116
	v_log_f32_e32 v115, v115
	s_nop 0
	v_mul_f32_e32 v116, 0x3f317217, v115
	v_fma_f32 v116, v115, s29, -v116
	v_fmac_f32_e32 v116, 0x3377d1cf, v115
	v_fmac_f32_e32 v116, 0x3f317217, v115
	v_cmp_lt_f32_e64 s[36:37], |v115|, s30
	s_nop 1
	v_cndmask_b32_e64 v115, v115, v116, s[36:37]
	v_cndmask_b32_e32 v116, 0, v180, vcc
	v_sub_f32_e32 v115, v115, v116
	v_sub_f32_e32 v27, v27, v115
	v_fma_f32 v27, v27, s13, 0
.LBB0_848:
	s_or_b64 exec, exec, s[0:1]
	v_cmp_le_i32_e32 vcc, s12, v114
	s_and_saveexec_b64 s[0:1], vcc
	s_cbranch_execz .LBB0_850
	s_add_i32 s13, 0, 0x1e000
	v_lshl_add_u32 v113, v23, 10, s13
	ds_read_b128 v[116:119], v113 offset:64
	ds_read_b128 v[120:123], v113 offset:80
	ds_read_b128 v[124:127], v113 offset:96
	ds_read_b128 v[128:131], v113 offset:112
	s_waitcnt lgkmcnt(3)
	v_mov_b32_e32 v132, v119
	s_waitcnt lgkmcnt(2)
	v_mov_b32_e32 v133, v123
	v_mov_b32_e32 v123, v120
	v_mov_b32_e32 v120, v117
	v_mov_b32_e32 v119, v122
	v_mov_b32_e32 v122, v116
	s_waitcnt vmcnt(39)
	v_pk_mul_f32 v[116:117], v[34:35], v[120:121]
	s_nop 0
	v_pk_fma_f32 v[116:117], v[28:29], v[122:123], v[116:117]
	s_waitcnt vmcnt(38)
	v_pk_fma_f32 v[116:117], v[30:31], v[118:119], v[116:117]
	s_waitcnt lgkmcnt(0)
	v_mov_b32_e32 v119, v128
	v_mov_b32_e32 v128, v125
	s_waitcnt vmcnt(37)
	v_pk_fma_f32 v[116:117], v[32:33], v[132:133], v[116:117]
	v_mov_b32_e32 v118, v124
	s_waitcnt vmcnt(31)
	v_pk_mul_f32 v[120:121], v[60:61], v[128:129]
	s_waitcnt vmcnt(28)
	v_add_f32_e32 v113, v41, v116
	v_mov_b32_e32 v116, v127
	v_mov_b32_e32 v127, v130
	v_pk_fma_f32 v[118:119], v[36:37], v[118:119], v[120:121]
	v_add_f32_e32 v113, v113, v117
	v_mov_b32_e32 v117, v131
	v_pk_fma_f32 v[118:119], v[38:39], v[126:127], v[118:119]
	s_nop 0
	v_pk_fma_f32 v[116:117], v[42:43], v[116:117], v[118:119]
	s_nop 0
	v_add_f32_e32 v113, v113, v116
	v_add_f32_e32 v113, v113, v117
	v_mul_f32_e64 v115, |v113|, s31
	v_exp_f32_e32 v115, v115
	v_min_f32_e32 v113, 0, v113
	v_add_f32_e32 v115, 1.0, v115
	v_cmp_gt_f32_e32 vcc, s28, v115
	s_nop 1
	v_cndmask_b32_e64 v116, 0, 32, vcc
	v_ldexp_f32 v115, v115, v116
	v_log_f32_e32 v115, v115
	s_nop 0
	v_mul_f32_e32 v116, 0x3f317217, v115
	v_fma_f32 v116, v115, s29, -v116
	v_fmac_f32_e32 v116, 0x3377d1cf, v115
	v_fmac_f32_e32 v116, 0x3f317217, v115
	v_cmp_lt_f32_e64 s[36:37], |v115|, s30
	s_nop 1
	v_cndmask_b32_e64 v115, v115, v116, s[36:37]
	v_cndmask_b32_e32 v116, 0, v180, vcc
	v_sub_f32_e32 v115, v115, v116
	v_sub_f32_e32 v113, v113, v115
	v_mul_f32_e32 v113, 0x3d800000, v113
.LBB0_850:
	s_or_b64 exec, exec, s[0:1]
	v_or_b32_e32 v117, 2, v114
	v_cmp_lt_i32_e32 vcc, s12, v117
	v_mov_b32_e32 v115, 0
	v_mov_b32_e32 v116, 0
	s_and_saveexec_b64 s[0:1], vcc
	s_cbranch_execz .LBB0_852
	v_lshl_add_u32 v116, v117, 6, 0
	v_add_u32_e32 v128, 0x1e000, v116
	ds_read_b128 v[116:119], v128
	ds_read_b128 v[120:123], v128 offset:16
	ds_read_b128 v[124:127], v128 offset:32
	ds_read_b128 v[128:131], v128 offset:48
	s_waitcnt lgkmcnt(3)
	v_mov_b32_e32 v132, v119
	s_waitcnt lgkmcnt(2)
	v_mov_b32_e32 v133, v123
	v_mov_b32_e32 v123, v120
	v_mov_b32_e32 v120, v117
	v_mov_b32_e32 v119, v122
	v_mov_b32_e32 v122, v116
	s_waitcnt vmcnt(39)
	v_pk_mul_f32 v[116:117], v[34:35], v[120:121]
	s_nop 0
	v_pk_fma_f32 v[116:117], v[28:29], v[122:123], v[116:117]
	s_waitcnt vmcnt(38)
	v_pk_fma_f32 v[116:117], v[30:31], v[118:119], v[116:117]
	s_waitcnt lgkmcnt(0)
	v_mov_b32_e32 v119, v128
	s_waitcnt vmcnt(37)
	v_pk_fma_f32 v[116:117], v[32:33], v[132:133], v[116:117]
	v_mov_b32_e32 v128, v125
	s_waitcnt vmcnt(28)
	v_add_f32_e32 v116, v41, v116
	v_mov_b32_e32 v118, v124
	v_pk_mul_f32 v[120:121], v[60:61], v[128:129]
	v_add_f32_e32 v122, v116, v117
	v_mov_b32_e32 v116, v127
	v_mov_b32_e32 v127, v130
	v_pk_fma_f32 v[118:119], v[36:37], v[118:119], v[120:121]
	v_mov_b32_e32 v117, v131
	v_pk_fma_f32 v[118:119], v[38:39], v[126:127], v[118:119]
	s_nop 0
	v_pk_fma_f32 v[116:117], v[42:43], v[116:117], v[118:119]
	s_nop 0
	v_add_f32_e32 v116, v122, v116
	v_add_f32_e32 v116, v116, v117
	v_mul_f32_e64 v117, |v116|, s31
	v_exp_f32_e32 v117, v117
	v_min_f32_e32 v116, 0, v116
	v_add_f32_e32 v117, 1.0, v117
	v_cmp_gt_f32_e32 vcc, s28, v117
	s_nop 1
	v_cndmask_b32_e64 v118, 0, 32, vcc
	v_ldexp_f32 v117, v117, v118
	v_log_f32_e32 v117, v117
	s_nop 0
	v_mul_f32_e32 v118, 0x3f317217, v117
	v_fma_f32 v118, v117, s29, -v118
	v_fmac_f32_e32 v118, 0x3377d1cf, v117
	v_fmac_f32_e32 v118, 0x3f317217, v117
	v_cmp_lt_f32_e64 s[36:37], |v117|, s30
	s_nop 1
	v_cndmask_b32_e64 v117, v117, v118, s[36:37]
	v_cndmask_b32_e32 v118, 0, v180, vcc
	v_sub_f32_e32 v117, v117, v118
	v_sub_f32_e32 v116, v116, v117
	v_mul_f32_e32 v116, 0x3d800000, v116
.LBB0_852:
	s_or_b64 exec, exec, s[0:1]
	v_or_b32_e32 v117, 3, v114
	v_cmp_lt_i32_e32 vcc, s12, v117
	s_and_saveexec_b64 s[0:1], vcc
	s_cbranch_execz .LBB0_854
	v_lshl_add_u32 v115, v117, 6, 0
	v_add_u32_e32 v115, 0x1e000, v115
	ds_read_b128 v[118:121], v115
	ds_read_b128 v[122:125], v115 offset:16
	ds_read_b128 v[126:129], v115 offset:32
	ds_read_b128 v[130:133], v115 offset:48
	s_waitcnt lgkmcnt(3)
	v_mov_b32_e32 v134, v121
	s_waitcnt lgkmcnt(2)
	v_mov_b32_e32 v135, v125
	v_mov_b32_e32 v125, v122
	v_mov_b32_e32 v122, v119
	v_mov_b32_e32 v121, v124
	v_mov_b32_e32 v124, v118
	s_waitcnt vmcnt(39)
	v_pk_mul_f32 v[118:119], v[34:35], v[122:123]
	s_nop 0
	v_pk_fma_f32 v[118:119], v[28:29], v[124:125], v[118:119]
	s_waitcnt vmcnt(38)
	v_pk_fma_f32 v[118:119], v[30:31], v[120:121], v[118:119]
	s_waitcnt lgkmcnt(0)
	v_mov_b32_e32 v121, v130
	v_mov_b32_e32 v130, v127
	s_waitcnt vmcnt(37)
	v_pk_fma_f32 v[118:119], v[32:33], v[134:135], v[118:119]
	v_mov_b32_e32 v120, v126
	s_waitcnt vmcnt(31)
	v_pk_mul_f32 v[122:123], v[60:61], v[130:131]
	s_waitcnt vmcnt(28)
	v_add_f32_e32 v115, v41, v118
	v_mov_b32_e32 v118, v129
	v_mov_b32_e32 v129, v132
	v_pk_fma_f32 v[120:121], v[36:37], v[120:121], v[122:123]
	v_add_f32_e32 v115, v115, v119
	v_mov_b32_e32 v119, v133
	v_pk_fma_f32 v[120:121], v[38:39], v[128:129], v[120:121]
	s_nop 0
	v_pk_fma_f32 v[118:119], v[42:43], v[118:119], v[120:121]
	s_nop 0
	v_add_f32_e32 v115, v115, v118
	v_add_f32_e32 v115, v115, v119
	v_mul_f32_e64 v117, |v115|, s31
	v_exp_f32_e32 v117, v117
	v_min_f32_e32 v115, 0, v115
	v_add_f32_e32 v117, 1.0, v117
	v_cmp_gt_f32_e32 vcc, s28, v117
	s_nop 1
	v_cndmask_b32_e64 v118, 0, 32, vcc
	v_ldexp_f32 v117, v117, v118
	v_log_f32_e32 v117, v117
	s_nop 0
	v_mul_f32_e32 v118, 0x3f317217, v117
	v_fma_f32 v118, v117, s29, -v118
	v_fmac_f32_e32 v118, 0x3377d1cf, v117
	v_fmac_f32_e32 v118, 0x3f317217, v117
	v_cmp_lt_f32_e64 s[36:37], |v117|, s30
	s_nop 1
	v_cndmask_b32_e64 v117, v117, v118, s[36:37]
	v_cndmask_b32_e32 v118, 0, v180, vcc
	v_sub_f32_e32 v117, v117, v118
	v_sub_f32_e32 v115, v115, v117
	v_mul_f32_e32 v115, 0x3d800000, v115
.LBB0_854:
	s_or_b64 exec, exec, s[0:1]
	v_or_b32_e32 v119, 4, v114
	v_cmp_lt_i32_e32 vcc, s12, v119
	v_mov_b32_e32 v117, 0
	v_mov_b32_e32 v118, 0
	s_and_saveexec_b64 s[0:1], vcc
	s_cbranch_execz .LBB0_856
	v_lshl_add_u32 v118, v119, 6, 0
	v_add_u32_e32 v130, 0x1e000, v118
	ds_read_b128 v[118:121], v130
	ds_read_b128 v[122:125], v130 offset:16
	ds_read_b128 v[126:129], v130 offset:32
	ds_read_b128 v[130:133], v130 offset:48
	s_waitcnt lgkmcnt(3)
	v_mov_b32_e32 v134, v121
	s_waitcnt lgkmcnt(2)
	v_mov_b32_e32 v135, v125
	v_mov_b32_e32 v125, v122
	v_mov_b32_e32 v122, v119
	v_mov_b32_e32 v121, v124
	v_mov_b32_e32 v124, v118
	s_waitcnt vmcnt(39)
	v_pk_mul_f32 v[118:119], v[34:35], v[122:123]
	s_nop 0
	v_pk_fma_f32 v[118:119], v[28:29], v[124:125], v[118:119]
	s_waitcnt vmcnt(38)
	v_pk_fma_f32 v[118:119], v[30:31], v[120:121], v[118:119]
	s_waitcnt lgkmcnt(0)
	v_mov_b32_e32 v121, v130
	s_waitcnt vmcnt(37)
	v_pk_fma_f32 v[118:119], v[32:33], v[134:135], v[118:119]
	v_mov_b32_e32 v130, v127
	s_waitcnt vmcnt(28)
	v_add_f32_e32 v118, v41, v118
	v_mov_b32_e32 v120, v126
	v_pk_mul_f32 v[122:123], v[60:61], v[130:131]
	v_add_f32_e32 v124, v118, v119
	v_mov_b32_e32 v118, v129
	v_mov_b32_e32 v129, v132
	v_pk_fma_f32 v[120:121], v[36:37], v[120:121], v[122:123]
	v_mov_b32_e32 v119, v133
	v_pk_fma_f32 v[120:121], v[38:39], v[128:129], v[120:121]
	s_nop 0
	v_pk_fma_f32 v[118:119], v[42:43], v[118:119], v[120:121]
	s_nop 0
	v_add_f32_e32 v118, v124, v118
	v_add_f32_e32 v118, v118, v119
	v_mul_f32_e64 v119, |v118|, s31
	v_exp_f32_e32 v119, v119
	v_min_f32_e32 v118, 0, v118
	v_add_f32_e32 v119, 1.0, v119
	v_cmp_gt_f32_e32 vcc, s28, v119
	s_nop 1
	v_cndmask_b32_e64 v120, 0, 32, vcc
	v_ldexp_f32 v119, v119, v120
	v_log_f32_e32 v119, v119
	s_nop 0
	v_mul_f32_e32 v120, 0x3f317217, v119
	v_fma_f32 v120, v119, s29, -v120
	v_fmac_f32_e32 v120, 0x3377d1cf, v119
	v_fmac_f32_e32 v120, 0x3f317217, v119
	v_cmp_lt_f32_e64 s[36:37], |v119|, s30
	s_nop 1
	v_cndmask_b32_e64 v119, v119, v120, s[36:37]
	v_cndmask_b32_e32 v120, 0, v180, vcc
	v_sub_f32_e32 v119, v119, v120
	v_sub_f32_e32 v118, v118, v119
	v_mul_f32_e32 v118, 0x3d800000, v118
.LBB0_856:
	s_or_b64 exec, exec, s[0:1]
	v_or_b32_e32 v119, 5, v114
	v_cmp_lt_i32_e32 vcc, s12, v119
	s_and_saveexec_b64 s[0:1], vcc
	s_cbranch_execz .LBB0_858
	v_lshl_add_u32 v117, v119, 6, 0
	v_add_u32_e32 v117, 0x1e000, v117
	ds_read_b128 v[120:123], v117
	ds_read_b128 v[124:127], v117 offset:16
	ds_read_b128 v[128:131], v117 offset:32
	ds_read_b128 v[132:135], v117 offset:48
	s_waitcnt lgkmcnt(3)
	v_mov_b32_e32 v152, v123
	s_waitcnt lgkmcnt(2)
	v_mov_b32_e32 v153, v127
	v_mov_b32_e32 v127, v124
	v_mov_b32_e32 v124, v121
	v_mov_b32_e32 v123, v126
	v_mov_b32_e32 v126, v120
	s_waitcnt vmcnt(39)
	v_pk_mul_f32 v[120:121], v[34:35], v[124:125]
	s_nop 0
	v_pk_fma_f32 v[120:121], v[28:29], v[126:127], v[120:121]
	s_waitcnt vmcnt(38)
	v_pk_fma_f32 v[120:121], v[30:31], v[122:123], v[120:121]
	s_waitcnt lgkmcnt(0)
	v_mov_b32_e32 v123, v132
	v_mov_b32_e32 v132, v129
	s_waitcnt vmcnt(37)
	v_pk_fma_f32 v[120:121], v[32:33], v[152:153], v[120:121]
	v_mov_b32_e32 v122, v128
	s_waitcnt vmcnt(31)
	v_pk_mul_f32 v[124:125], v[60:61], v[132:133]
	s_waitcnt vmcnt(28)
	v_add_f32_e32 v117, v41, v120
	v_mov_b32_e32 v120, v131
	v_mov_b32_e32 v131, v134
	v_pk_fma_f32 v[122:123], v[36:37], v[122:123], v[124:125]
	v_add_f32_e32 v117, v117, v121
	v_mov_b32_e32 v121, v135
	v_pk_fma_f32 v[122:123], v[38:39], v[130:131], v[122:123]
	s_nop 0
	v_pk_fma_f32 v[120:121], v[42:43], v[120:121], v[122:123]
	s_nop 0
	v_add_f32_e32 v117, v117, v120
	v_add_f32_e32 v117, v117, v121
	v_mul_f32_e64 v119, |v117|, s31
	v_exp_f32_e32 v119, v119
	v_min_f32_e32 v117, 0, v117
	v_add_f32_e32 v119, 1.0, v119
	v_cmp_gt_f32_e32 vcc, s28, v119
	s_nop 1
	v_cndmask_b32_e64 v120, 0, 32, vcc
	v_ldexp_f32 v119, v119, v120
	v_log_f32_e32 v119, v119
	s_nop 0
	v_mul_f32_e32 v120, 0x3f317217, v119
	v_fma_f32 v120, v119, s29, -v120
	v_fmac_f32_e32 v120, 0x3377d1cf, v119
	v_fmac_f32_e32 v120, 0x3f317217, v119
	v_cmp_lt_f32_e64 s[36:37], |v119|, s30
	s_nop 1
	v_cndmask_b32_e64 v119, v119, v120, s[36:37]
	v_cndmask_b32_e32 v120, 0, v180, vcc
	v_sub_f32_e32 v119, v119, v120
	v_sub_f32_e32 v117, v117, v119
	v_mul_f32_e32 v117, 0x3d800000, v117
.LBB0_858:
	s_or_b64 exec, exec, s[0:1]
	v_or_b32_e32 v121, 6, v114
	v_cmp_lt_i32_e32 vcc, s12, v121
	v_mov_b32_e32 v119, 0
	v_mov_b32_e32 v120, 0
	s_and_saveexec_b64 s[0:1], vcc
	s_cbranch_execz .LBB0_860
	v_lshl_add_u32 v120, v121, 6, 0
	v_add_u32_e32 v132, 0x1e000, v120
	ds_read_b128 v[120:123], v132
	ds_read_b128 v[124:127], v132 offset:16
	ds_read_b128 v[128:131], v132 offset:32
	ds_read_b128 v[132:135], v132 offset:48
	s_waitcnt lgkmcnt(3)
	v_mov_b32_e32 v152, v123
	s_waitcnt lgkmcnt(2)
	v_mov_b32_e32 v153, v127
	v_mov_b32_e32 v127, v124
	v_mov_b32_e32 v124, v121
	v_mov_b32_e32 v123, v126
	v_mov_b32_e32 v126, v120
	s_waitcnt vmcnt(39)
	v_pk_mul_f32 v[120:121], v[34:35], v[124:125]
	s_nop 0
	v_pk_fma_f32 v[120:121], v[28:29], v[126:127], v[120:121]
	s_waitcnt vmcnt(38)
	v_pk_fma_f32 v[120:121], v[30:31], v[122:123], v[120:121]
	s_waitcnt lgkmcnt(0)
	v_mov_b32_e32 v123, v132
	s_waitcnt vmcnt(37)
	v_pk_fma_f32 v[120:121], v[32:33], v[152:153], v[120:121]
	v_mov_b32_e32 v132, v129
	s_waitcnt vmcnt(28)
	v_add_f32_e32 v120, v41, v120
	v_mov_b32_e32 v122, v128
	v_pk_mul_f32 v[124:125], v[60:61], v[132:133]
	v_add_f32_e32 v126, v120, v121
	v_mov_b32_e32 v120, v131
	v_mov_b32_e32 v131, v134
	v_pk_fma_f32 v[122:123], v[36:37], v[122:123], v[124:125]
	v_mov_b32_e32 v121, v135
	v_pk_fma_f32 v[122:123], v[38:39], v[130:131], v[122:123]
	s_nop 0
	v_pk_fma_f32 v[120:121], v[42:43], v[120:121], v[122:123]
	s_nop 0
	v_add_f32_e32 v120, v126, v120
	v_add_f32_e32 v120, v120, v121
	v_mul_f32_e64 v121, |v120|, s31
	v_exp_f32_e32 v121, v121
	v_min_f32_e32 v120, 0, v120
	v_add_f32_e32 v121, 1.0, v121
	v_cmp_gt_f32_e32 vcc, s28, v121
	s_nop 1
	v_cndmask_b32_e64 v122, 0, 32, vcc
	v_ldexp_f32 v121, v121, v122
	v_log_f32_e32 v121, v121
	s_nop 0
	v_mul_f32_e32 v122, 0x3f317217, v121
	v_fma_f32 v122, v121, s29, -v122
	v_fmac_f32_e32 v122, 0x3377d1cf, v121
	v_fmac_f32_e32 v122, 0x3f317217, v121
	v_cmp_lt_f32_e64 s[36:37], |v121|, s30
	s_nop 1
	v_cndmask_b32_e64 v121, v121, v122, s[36:37]
	v_cndmask_b32_e32 v122, 0, v180, vcc
	v_sub_f32_e32 v121, v121, v122
	v_sub_f32_e32 v120, v120, v121
	v_mul_f32_e32 v120, 0x3d800000, v120
.LBB0_860:
	s_or_b64 exec, exec, s[0:1]
	v_or_b32_e32 v121, 7, v114
	v_cmp_lt_i32_e32 vcc, s12, v121
	s_and_saveexec_b64 s[0:1], vcc
	s_cbranch_execz .LBB0_862
	v_lshl_add_u32 v119, v121, 6, 0
	v_add_u32_e32 v119, 0x1e000, v119
	ds_read_b128 v[122:125], v119
	ds_read_b128 v[126:129], v119 offset:16
	ds_read_b128 v[130:133], v119 offset:32
	ds_read_b128 v[152:155], v119 offset:48
	s_waitcnt lgkmcnt(3)
	v_mov_b32_e32 v134, v125
	s_waitcnt lgkmcnt(2)
	v_mov_b32_e32 v135, v129
	v_mov_b32_e32 v129, v126
	v_mov_b32_e32 v126, v123
	v_mov_b32_e32 v125, v128
	v_mov_b32_e32 v128, v122
	s_waitcnt vmcnt(39)
	v_pk_mul_f32 v[122:123], v[34:35], v[126:127]
	s_nop 0
	v_pk_fma_f32 v[122:123], v[28:29], v[128:129], v[122:123]
	s_waitcnt vmcnt(38)
	v_pk_fma_f32 v[122:123], v[30:31], v[124:125], v[122:123]
	s_waitcnt lgkmcnt(0)
	v_mov_b32_e32 v125, v152
	v_mov_b32_e32 v152, v131
	s_waitcnt vmcnt(37)
	v_pk_fma_f32 v[122:123], v[32:33], v[134:135], v[122:123]
	v_mov_b32_e32 v124, v130
	s_waitcnt vmcnt(31)
	v_pk_mul_f32 v[126:127], v[60:61], v[152:153]
	s_waitcnt vmcnt(28)
	v_add_f32_e32 v119, v41, v122
	v_mov_b32_e32 v122, v133
	v_mov_b32_e32 v133, v154
	v_pk_fma_f32 v[124:125], v[36:37], v[124:125], v[126:127]
	v_add_f32_e32 v119, v119, v123
	v_mov_b32_e32 v123, v155
	v_pk_fma_f32 v[124:125], v[38:39], v[132:133], v[124:125]
	s_nop 0
	v_pk_fma_f32 v[122:123], v[42:43], v[122:123], v[124:125]
	s_nop 0
	v_add_f32_e32 v119, v119, v122
	v_add_f32_e32 v119, v119, v123
	v_mul_f32_e64 v121, |v119|, s31
	v_exp_f32_e32 v121, v121
	v_min_f32_e32 v119, 0, v119
	v_add_f32_e32 v121, 1.0, v121
	v_cmp_gt_f32_e32 vcc, s28, v121
	s_nop 1
	v_cndmask_b32_e64 v122, 0, 32, vcc
	v_ldexp_f32 v121, v121, v122
	v_log_f32_e32 v121, v121
	s_nop 0
	v_mul_f32_e32 v122, 0x3f317217, v121
	v_fma_f32 v122, v121, s29, -v122
	v_fmac_f32_e32 v122, 0x3377d1cf, v121
	v_fmac_f32_e32 v122, 0x3f317217, v121
	v_cmp_lt_f32_e64 s[36:37], |v121|, s30
	s_nop 1
	v_cndmask_b32_e64 v121, v121, v122, s[36:37]
	v_cndmask_b32_e32 v122, 0, v180, vcc
	v_sub_f32_e32 v121, v121, v122
	v_sub_f32_e32 v119, v119, v121
	v_mul_f32_e32 v119, 0x3d800000, v119
.LBB0_862:
	s_or_b64 exec, exec, s[0:1]
	v_or_b32_e32 v123, 8, v114
	v_cmp_lt_i32_e32 vcc, s12, v123
	v_mov_b32_e32 v121, 0
	v_mov_b32_e32 v122, 0
	s_and_saveexec_b64 s[0:1], vcc
	s_cbranch_execz .LBB0_864
	v_lshl_add_u32 v122, v123, 6, 0
	v_add_u32_e32 v134, 0x1e000, v122
	ds_read_b128 v[122:125], v134
	ds_read_b128 v[126:129], v134 offset:16
	ds_read_b128 v[130:133], v134 offset:32
	ds_read_b128 v[152:155], v134 offset:48
	s_waitcnt lgkmcnt(3)
	v_mov_b32_e32 v134, v125
	s_waitcnt lgkmcnt(2)
	v_mov_b32_e32 v135, v129
	v_mov_b32_e32 v129, v126
	v_mov_b32_e32 v126, v123
	v_mov_b32_e32 v125, v128
	v_mov_b32_e32 v128, v122
	s_waitcnt vmcnt(39)
	v_pk_mul_f32 v[122:123], v[34:35], v[126:127]
	s_nop 0
	v_pk_fma_f32 v[122:123], v[28:29], v[128:129], v[122:123]
	s_waitcnt vmcnt(38)
	v_pk_fma_f32 v[122:123], v[30:31], v[124:125], v[122:123]
	s_waitcnt lgkmcnt(0)
	v_mov_b32_e32 v125, v152
	s_waitcnt vmcnt(37)
	v_pk_fma_f32 v[122:123], v[32:33], v[134:135], v[122:123]
	v_mov_b32_e32 v152, v131
	s_waitcnt vmcnt(28)
	v_add_f32_e32 v122, v41, v122
	v_mov_b32_e32 v124, v130
	v_pk_mul_f32 v[126:127], v[60:61], v[152:153]
	v_add_f32_e32 v128, v122, v123
	v_mov_b32_e32 v122, v133
	v_mov_b32_e32 v133, v154
	v_pk_fma_f32 v[124:125], v[36:37], v[124:125], v[126:127]
	v_mov_b32_e32 v123, v155
	v_pk_fma_f32 v[124:125], v[38:39], v[132:133], v[124:125]
	s_nop 0
	v_pk_fma_f32 v[122:123], v[42:43], v[122:123], v[124:125]
	s_nop 0
	v_add_f32_e32 v122, v128, v122
	v_add_f32_e32 v122, v122, v123
	v_mul_f32_e64 v123, |v122|, s31
	v_exp_f32_e32 v123, v123
	v_min_f32_e32 v122, 0, v122
	v_add_f32_e32 v123, 1.0, v123
	v_cmp_gt_f32_e32 vcc, s28, v123
	s_nop 1
	v_cndmask_b32_e64 v124, 0, 32, vcc
	v_ldexp_f32 v123, v123, v124
	v_log_f32_e32 v123, v123
	s_nop 0
	v_mul_f32_e32 v124, 0x3f317217, v123
	v_fma_f32 v124, v123, s29, -v124
	v_fmac_f32_e32 v124, 0x3377d1cf, v123
	v_fmac_f32_e32 v124, 0x3f317217, v123
	v_cmp_lt_f32_e64 s[36:37], |v123|, s30
	s_nop 1
	v_cndmask_b32_e64 v123, v123, v124, s[36:37]
	v_cndmask_b32_e32 v124, 0, v180, vcc
	v_sub_f32_e32 v123, v123, v124
	v_sub_f32_e32 v122, v122, v123
	v_mul_f32_e32 v122, 0x3d800000, v122
.LBB0_864:
	s_or_b64 exec, exec, s[0:1]
	v_or_b32_e32 v123, 9, v114
	v_cmp_lt_i32_e32 vcc, s12, v123
	s_and_saveexec_b64 s[0:1], vcc
	s_cbranch_execz .LBB0_866
	v_lshl_add_u32 v121, v123, 6, 0
	v_add_u32_e32 v121, 0x1e000, v121
	ds_read_b128 v[124:127], v121
	ds_read_b128 v[128:131], v121 offset:16
	ds_read_b128 v[132:135], v121 offset:32
	ds_read_b128 v[152:155], v121 offset:48
	s_waitcnt lgkmcnt(3)
	v_mov_b32_e32 v156, v127
	s_waitcnt lgkmcnt(2)
	v_mov_b32_e32 v157, v131
	v_mov_b32_e32 v131, v128
	v_mov_b32_e32 v128, v125
	v_mov_b32_e32 v127, v130
	v_mov_b32_e32 v130, v124
	s_waitcnt vmcnt(39)
	v_pk_mul_f32 v[124:125], v[34:35], v[128:129]
	s_nop 0
	v_pk_fma_f32 v[124:125], v[28:29], v[130:131], v[124:125]
	s_waitcnt vmcnt(38)
	v_pk_fma_f32 v[124:125], v[30:31], v[126:127], v[124:125]
	s_waitcnt lgkmcnt(0)
	v_mov_b32_e32 v127, v152
	v_mov_b32_e32 v152, v133
	s_waitcnt vmcnt(37)
	v_pk_fma_f32 v[124:125], v[32:33], v[156:157], v[124:125]
	v_mov_b32_e32 v126, v132
	s_waitcnt vmcnt(31)
	v_pk_mul_f32 v[128:129], v[60:61], v[152:153]
	s_waitcnt vmcnt(28)
	v_add_f32_e32 v121, v41, v124
	v_mov_b32_e32 v124, v135
	v_mov_b32_e32 v135, v154
	v_pk_fma_f32 v[126:127], v[36:37], v[126:127], v[128:129]
	v_add_f32_e32 v121, v121, v125
	v_mov_b32_e32 v125, v155
	v_pk_fma_f32 v[126:127], v[38:39], v[134:135], v[126:127]
	s_nop 0
	v_pk_fma_f32 v[124:125], v[42:43], v[124:125], v[126:127]
	s_nop 0
	v_add_f32_e32 v121, v121, v124
	v_add_f32_e32 v121, v121, v125
	v_mul_f32_e64 v123, |v121|, s31
	v_exp_f32_e32 v123, v123
	v_min_f32_e32 v121, 0, v121
	v_add_f32_e32 v123, 1.0, v123
	v_cmp_gt_f32_e32 vcc, s28, v123
	s_nop 1
	v_cndmask_b32_e64 v124, 0, 32, vcc
	v_ldexp_f32 v123, v123, v124
	v_log_f32_e32 v123, v123
	s_nop 0
	v_mul_f32_e32 v124, 0x3f317217, v123
	v_fma_f32 v124, v123, s29, -v124
	v_fmac_f32_e32 v124, 0x3377d1cf, v123
	v_fmac_f32_e32 v124, 0x3f317217, v123
	v_cmp_lt_f32_e64 s[36:37], |v123|, s30
	s_nop 1
	v_cndmask_b32_e64 v123, v123, v124, s[36:37]
	v_cndmask_b32_e32 v124, 0, v180, vcc
	v_sub_f32_e32 v123, v123, v124
	v_sub_f32_e32 v121, v121, v123
	v_mul_f32_e32 v121, 0x3d800000, v121
.LBB0_866:
	s_or_b64 exec, exec, s[0:1]
	v_or_b32_e32 v125, 10, v114
	v_cmp_lt_i32_e32 vcc, s12, v125
	v_mov_b32_e32 v123, 0
	v_mov_b32_e32 v124, 0
	s_and_saveexec_b64 s[0:1], vcc
	s_cbranch_execz .LBB0_868
	v_lshl_add_u32 v124, v125, 6, 0
	v_add_u32_e32 v152, 0x1e000, v124
	ds_read_b128 v[124:127], v152
	ds_read_b128 v[128:131], v152 offset:16
	ds_read_b128 v[132:135], v152 offset:32
	ds_read_b128 v[152:155], v152 offset:48
	s_waitcnt lgkmcnt(3)
	v_mov_b32_e32 v156, v127
	s_waitcnt lgkmcnt(2)
	v_mov_b32_e32 v157, v131
	v_mov_b32_e32 v131, v128
	v_mov_b32_e32 v128, v125
	v_mov_b32_e32 v127, v130
	v_mov_b32_e32 v130, v124
	s_waitcnt vmcnt(39)
	v_pk_mul_f32 v[124:125], v[34:35], v[128:129]
	s_nop 0
	v_pk_fma_f32 v[124:125], v[28:29], v[130:131], v[124:125]
	s_waitcnt vmcnt(38)
	v_pk_fma_f32 v[124:125], v[30:31], v[126:127], v[124:125]
	s_waitcnt lgkmcnt(0)
	v_mov_b32_e32 v127, v152
	s_waitcnt vmcnt(37)
	v_pk_fma_f32 v[124:125], v[32:33], v[156:157], v[124:125]
	v_mov_b32_e32 v152, v133
	s_waitcnt vmcnt(28)
	v_add_f32_e32 v124, v41, v124
	v_mov_b32_e32 v126, v132
	v_pk_mul_f32 v[128:129], v[60:61], v[152:153]
	v_add_f32_e32 v130, v124, v125
	v_mov_b32_e32 v124, v135
	v_mov_b32_e32 v135, v154
	v_pk_fma_f32 v[126:127], v[36:37], v[126:127], v[128:129]
	v_mov_b32_e32 v125, v155
	v_pk_fma_f32 v[126:127], v[38:39], v[134:135], v[126:127]
	s_nop 0
	v_pk_fma_f32 v[124:125], v[42:43], v[124:125], v[126:127]
	s_nop 0
	v_add_f32_e32 v124, v130, v124
	v_add_f32_e32 v124, v124, v125
	v_mul_f32_e64 v125, |v124|, s31
	v_exp_f32_e32 v125, v125
	v_min_f32_e32 v124, 0, v124
	v_add_f32_e32 v125, 1.0, v125
	v_cmp_gt_f32_e32 vcc, s28, v125
	s_nop 1
	v_cndmask_b32_e64 v126, 0, 32, vcc
	v_ldexp_f32 v125, v125, v126
	v_log_f32_e32 v125, v125
	s_nop 0
	v_mul_f32_e32 v126, 0x3f317217, v125
	v_fma_f32 v126, v125, s29, -v126
	v_fmac_f32_e32 v126, 0x3377d1cf, v125
	v_fmac_f32_e32 v126, 0x3f317217, v125
	v_cmp_lt_f32_e64 s[36:37], |v125|, s30
	s_nop 1
	v_cndmask_b32_e64 v125, v125, v126, s[36:37]
	v_cndmask_b32_e32 v126, 0, v180, vcc
	v_sub_f32_e32 v125, v125, v126
	v_sub_f32_e32 v124, v124, v125
	v_mul_f32_e32 v124, 0x3d800000, v124
.LBB0_868:
	s_or_b64 exec, exec, s[0:1]
	v_or_b32_e32 v125, 11, v114
	v_cmp_lt_i32_e32 vcc, s12, v125
	s_and_saveexec_b64 s[0:1], vcc
	s_cbranch_execz .LBB0_870
	v_lshl_add_u32 v123, v125, 6, 0
	v_add_u32_e32 v123, 0x1e000, v123
	ds_read_b128 v[126:129], v123
	ds_read_b128 v[130:133], v123 offset:16
	ds_read_b128 v[152:155], v123 offset:32
	ds_read_b128 v[156:159], v123 offset:48
	s_waitcnt lgkmcnt(3)
	v_mov_b32_e32 v134, v129
	s_waitcnt lgkmcnt(2)
	v_mov_b32_e32 v135, v133
	v_mov_b32_e32 v133, v130
	v_mov_b32_e32 v130, v127
	v_mov_b32_e32 v129, v132
	v_mov_b32_e32 v132, v126
	s_waitcnt vmcnt(39)
	v_pk_mul_f32 v[126:127], v[34:35], v[130:131]
	s_nop 0
	v_pk_fma_f32 v[126:127], v[28:29], v[132:133], v[126:127]
	s_waitcnt vmcnt(38)
	v_pk_fma_f32 v[126:127], v[30:31], v[128:129], v[126:127]
	s_waitcnt lgkmcnt(0)
	v_mov_b32_e32 v129, v156
	v_mov_b32_e32 v156, v153
	s_waitcnt vmcnt(37)
	v_pk_fma_f32 v[126:127], v[32:33], v[134:135], v[126:127]
	v_mov_b32_e32 v128, v152
	s_waitcnt vmcnt(31)
	v_pk_mul_f32 v[130:131], v[60:61], v[156:157]
	s_waitcnt vmcnt(28)
	v_add_f32_e32 v123, v41, v126
	v_mov_b32_e32 v126, v155
	v_mov_b32_e32 v155, v158
	v_pk_fma_f32 v[128:129], v[36:37], v[128:129], v[130:131]
	v_add_f32_e32 v123, v123, v127
	v_mov_b32_e32 v127, v159
	v_pk_fma_f32 v[128:129], v[38:39], v[154:155], v[128:129]
	s_nop 0
	v_pk_fma_f32 v[126:127], v[42:43], v[126:127], v[128:129]
	s_nop 0
	v_add_f32_e32 v123, v123, v126
	v_add_f32_e32 v123, v123, v127
	v_mul_f32_e64 v125, |v123|, s31
	v_exp_f32_e32 v125, v125
	v_min_f32_e32 v123, 0, v123
	v_add_f32_e32 v125, 1.0, v125
	v_cmp_gt_f32_e32 vcc, s28, v125
	s_nop 1
	v_cndmask_b32_e64 v126, 0, 32, vcc
	v_ldexp_f32 v125, v125, v126
	v_log_f32_e32 v125, v125
	s_nop 0
	v_mul_f32_e32 v126, 0x3f317217, v125
	v_fma_f32 v126, v125, s29, -v126
	v_fmac_f32_e32 v126, 0x3377d1cf, v125
	v_fmac_f32_e32 v126, 0x3f317217, v125
	v_cmp_lt_f32_e64 s[36:37], |v125|, s30
	s_nop 1
	v_cndmask_b32_e64 v125, v125, v126, s[36:37]
	v_cndmask_b32_e32 v126, 0, v180, vcc
	v_sub_f32_e32 v125, v125, v126
	v_sub_f32_e32 v123, v123, v125
	v_mul_f32_e32 v123, 0x3d800000, v123
.LBB0_870:
	s_or_b64 exec, exec, s[0:1]
	v_or_b32_e32 v127, 12, v114
	v_cmp_lt_i32_e32 vcc, s12, v127
	v_mov_b32_e32 v125, 0
	v_mov_b32_e32 v126, 0
	s_and_saveexec_b64 s[0:1], vcc
	s_cbranch_execz .LBB0_872
	v_lshl_add_u32 v126, v127, 6, 0
	v_add_u32_e32 v134, 0x1e000, v126
	ds_read_b128 v[126:129], v134
	ds_read_b128 v[130:133], v134 offset:16
	ds_read_b128 v[152:155], v134 offset:32
	ds_read_b128 v[156:159], v134 offset:48
	s_waitcnt lgkmcnt(3)
	v_mov_b32_e32 v134, v129
	s_waitcnt lgkmcnt(2)
	v_mov_b32_e32 v135, v133
	v_mov_b32_e32 v133, v130
	v_mov_b32_e32 v130, v127
	v_mov_b32_e32 v129, v132
	v_mov_b32_e32 v132, v126
	s_waitcnt vmcnt(39)
	v_pk_mul_f32 v[126:127], v[34:35], v[130:131]
	s_nop 0
	v_pk_fma_f32 v[126:127], v[28:29], v[132:133], v[126:127]
	s_waitcnt vmcnt(38)
	v_pk_fma_f32 v[126:127], v[30:31], v[128:129], v[126:127]
	s_waitcnt lgkmcnt(0)
	v_mov_b32_e32 v129, v156
	s_waitcnt vmcnt(37)
	v_pk_fma_f32 v[126:127], v[32:33], v[134:135], v[126:127]
	v_mov_b32_e32 v156, v153
	s_waitcnt vmcnt(28)
	v_add_f32_e32 v126, v41, v126
	v_mov_b32_e32 v128, v152
	v_pk_mul_f32 v[130:131], v[60:61], v[156:157]
	v_add_f32_e32 v132, v126, v127
	v_mov_b32_e32 v126, v155
	v_mov_b32_e32 v155, v158
	v_pk_fma_f32 v[128:129], v[36:37], v[128:129], v[130:131]
	v_mov_b32_e32 v127, v159
	v_pk_fma_f32 v[128:129], v[38:39], v[154:155], v[128:129]
	s_nop 0
	v_pk_fma_f32 v[126:127], v[42:43], v[126:127], v[128:129]
	s_nop 0
	v_add_f32_e32 v126, v132, v126
	v_add_f32_e32 v126, v126, v127
	v_mul_f32_e64 v127, |v126|, s31
	v_exp_f32_e32 v127, v127
	v_min_f32_e32 v126, 0, v126
	v_add_f32_e32 v127, 1.0, v127
	v_cmp_gt_f32_e32 vcc, s28, v127
	s_nop 1
	v_cndmask_b32_e64 v128, 0, 32, vcc
	v_ldexp_f32 v127, v127, v128
	v_log_f32_e32 v127, v127
	s_nop 0
	v_mul_f32_e32 v128, 0x3f317217, v127
	v_fma_f32 v128, v127, s29, -v128
	v_fmac_f32_e32 v128, 0x3377d1cf, v127
	v_fmac_f32_e32 v128, 0x3f317217, v127
	v_cmp_lt_f32_e64 s[36:37], |v127|, s30
	s_nop 1
	v_cndmask_b32_e64 v127, v127, v128, s[36:37]
	v_cndmask_b32_e32 v128, 0, v180, vcc
	v_sub_f32_e32 v127, v127, v128
	v_sub_f32_e32 v126, v126, v127
	v_mul_f32_e32 v126, 0x3d800000, v126
.LBB0_872:
	s_or_b64 exec, exec, s[0:1]
	v_or_b32_e32 v127, 13, v114
	v_cmp_lt_i32_e32 vcc, s12, v127
	s_and_saveexec_b64 s[0:1], vcc
	s_cbranch_execz .LBB0_874
	v_lshl_add_u32 v125, v127, 6, 0
	v_add_u32_e32 v125, 0x1e000, v125
	ds_read_b128 v[128:131], v125
	ds_read_b128 v[132:135], v125 offset:16
	ds_read_b128 v[152:155], v125 offset:32
	ds_read_b128 v[156:159], v125 offset:48
	s_waitcnt lgkmcnt(3)
	v_mov_b32_e32 v160, v131
	s_waitcnt lgkmcnt(2)
	v_mov_b32_e32 v161, v135
	v_mov_b32_e32 v135, v132
	v_mov_b32_e32 v132, v129
	v_mov_b32_e32 v131, v134
	v_mov_b32_e32 v134, v128
	s_waitcnt vmcnt(39)
	v_pk_mul_f32 v[128:129], v[34:35], v[132:133]
	s_nop 0
	v_pk_fma_f32 v[128:129], v[28:29], v[134:135], v[128:129]
	s_waitcnt vmcnt(38)
	v_pk_fma_f32 v[128:129], v[30:31], v[130:131], v[128:129]
	s_waitcnt lgkmcnt(0)
	v_mov_b32_e32 v131, v156
	v_mov_b32_e32 v156, v153
	s_waitcnt vmcnt(37)
	v_pk_fma_f32 v[128:129], v[32:33], v[160:161], v[128:129]
	v_mov_b32_e32 v130, v152
	s_waitcnt vmcnt(31)
	v_pk_mul_f32 v[132:133], v[60:61], v[156:157]
	s_waitcnt vmcnt(28)
	v_add_f32_e32 v125, v41, v128
	v_mov_b32_e32 v128, v155
	v_mov_b32_e32 v155, v158
	v_pk_fma_f32 v[130:131], v[36:37], v[130:131], v[132:133]
	v_add_f32_e32 v125, v125, v129
	v_mov_b32_e32 v129, v159
	v_pk_fma_f32 v[130:131], v[38:39], v[154:155], v[130:131]
	s_nop 0
	v_pk_fma_f32 v[128:129], v[42:43], v[128:129], v[130:131]
	s_nop 0
	v_add_f32_e32 v125, v125, v128
	v_add_f32_e32 v125, v125, v129
	v_mul_f32_e64 v127, |v125|, s31
	v_exp_f32_e32 v127, v127
	v_min_f32_e32 v125, 0, v125
	v_add_f32_e32 v127, 1.0, v127
	v_cmp_gt_f32_e32 vcc, s28, v127
	s_nop 1
	v_cndmask_b32_e64 v128, 0, 32, vcc
	v_ldexp_f32 v127, v127, v128
	v_log_f32_e32 v127, v127
	s_nop 0
	v_mul_f32_e32 v128, 0x3f317217, v127
	v_fma_f32 v128, v127, s29, -v128
	v_fmac_f32_e32 v128, 0x3377d1cf, v127
	v_fmac_f32_e32 v128, 0x3f317217, v127
	v_cmp_lt_f32_e64 s[36:37], |v127|, s30
	s_nop 1
	v_cndmask_b32_e64 v127, v127, v128, s[36:37]
	v_cndmask_b32_e32 v128, 0, v180, vcc
	v_sub_f32_e32 v127, v127, v128
	v_sub_f32_e32 v125, v125, v127
	v_mul_f32_e32 v125, 0x3d800000, v125
.LBB0_874:
	s_or_b64 exec, exec, s[0:1]
	v_or_b32_e32 v129, 14, v114
	v_cmp_lt_i32_e32 vcc, s12, v129
	v_mov_b32_e32 v127, 0
	v_mov_b32_e32 v128, 0
	s_and_saveexec_b64 s[0:1], vcc
	s_cbranch_execz .LBB0_876
	v_lshl_add_u32 v128, v129, 6, 0
	v_add_u32_e32 v156, 0x1e000, v128
	ds_read_b128 v[128:131], v156
	ds_read_b128 v[132:135], v156 offset:16
	ds_read_b128 v[152:155], v156 offset:32
	ds_read_b128 v[156:159], v156 offset:48
	s_waitcnt lgkmcnt(3)
	v_mov_b32_e32 v160, v131
	s_waitcnt lgkmcnt(2)
	v_mov_b32_e32 v161, v135
	v_mov_b32_e32 v135, v132
	v_mov_b32_e32 v132, v129
	v_mov_b32_e32 v131, v134
	v_mov_b32_e32 v134, v128
	s_waitcnt vmcnt(39)
	v_pk_mul_f32 v[128:129], v[34:35], v[132:133]
	s_nop 0
	v_pk_fma_f32 v[128:129], v[28:29], v[134:135], v[128:129]
	s_waitcnt vmcnt(38)
	v_pk_fma_f32 v[128:129], v[30:31], v[130:131], v[128:129]
	s_waitcnt lgkmcnt(0)
	v_mov_b32_e32 v131, v156
	s_waitcnt vmcnt(37)
	v_pk_fma_f32 v[128:129], v[32:33], v[160:161], v[128:129]
	v_mov_b32_e32 v156, v153
	s_waitcnt vmcnt(28)
	v_add_f32_e32 v128, v41, v128
	v_mov_b32_e32 v130, v152
	v_pk_mul_f32 v[132:133], v[60:61], v[156:157]
	v_add_f32_e32 v134, v128, v129
	v_mov_b32_e32 v128, v155
	v_mov_b32_e32 v155, v158
	v_pk_fma_f32 v[130:131], v[36:37], v[130:131], v[132:133]
	v_mov_b32_e32 v129, v159
	v_pk_fma_f32 v[130:131], v[38:39], v[154:155], v[130:131]
	s_nop 0
	v_pk_fma_f32 v[128:129], v[42:43], v[128:129], v[130:131]
	s_nop 0
	v_add_f32_e32 v128, v134, v128
	v_add_f32_e32 v128, v128, v129
	v_mul_f32_e64 v129, |v128|, s31
	v_exp_f32_e32 v129, v129
	v_min_f32_e32 v128, 0, v128
	v_add_f32_e32 v129, 1.0, v129
	v_cmp_gt_f32_e32 vcc, s28, v129
	s_nop 1
	v_cndmask_b32_e64 v130, 0, 32, vcc
	v_ldexp_f32 v129, v129, v130
	v_log_f32_e32 v129, v129
	s_nop 0
	v_mul_f32_e32 v130, 0x3f317217, v129
	v_fma_f32 v130, v129, s29, -v130
	v_fmac_f32_e32 v130, 0x3377d1cf, v129
	v_fmac_f32_e32 v130, 0x3f317217, v129
	v_cmp_lt_f32_e64 s[36:37], |v129|, s30
	s_nop 1
	v_cndmask_b32_e64 v129, v129, v130, s[36:37]
	v_cndmask_b32_e32 v130, 0, v180, vcc
	v_sub_f32_e32 v129, v129, v130
	v_sub_f32_e32 v128, v128, v129
	v_mul_f32_e32 v128, 0x3d800000, v128
.LBB0_876:
	s_or_b64 exec, exec, s[0:1]
	v_or_b32_e32 v114, 15, v114
	v_cmp_lt_i32_e32 vcc, s12, v114
	s_and_saveexec_b64 s[0:1], vcc
	s_cbranch_execz .LBB0_878
	v_lshl_add_u32 v114, v114, 6, 0
	v_add_u32_e32 v114, 0x1e000, v114
	ds_read_b128 v[130:133], v114
	ds_read_b128 v[152:155], v114 offset:16
	ds_read_b128 v[156:159], v114 offset:32
	ds_read_b128 v[160:163], v114 offset:48
	s_waitcnt lgkmcnt(3)
	v_mov_b32_e32 v134, v133
	s_waitcnt lgkmcnt(2)
	v_mov_b32_e32 v135, v155
	v_mov_b32_e32 v155, v152
	v_mov_b32_e32 v152, v131
	v_mov_b32_e32 v133, v154
	v_mov_b32_e32 v154, v130
	s_waitcnt vmcnt(39)
	v_pk_mul_f32 v[34:35], v[34:35], v[152:153]
	s_nop 0
	v_pk_fma_f32 v[28:29], v[28:29], v[154:155], v[34:35]
	s_waitcnt vmcnt(38)
	v_pk_fma_f32 v[28:29], v[30:31], v[132:133], v[28:29]
	s_waitcnt lgkmcnt(0)
	v_mov_b32_e32 v31, v160
	s_waitcnt vmcnt(37)
	v_pk_fma_f32 v[28:29], v[32:33], v[134:135], v[28:29]
	v_mov_b32_e32 v160, v157
	s_waitcnt vmcnt(28)
	v_add_f32_e32 v28, v41, v28
	v_mov_b32_e32 v30, v156
	v_pk_mul_f32 v[32:33], v[60:61], v[160:161]
	v_add_f32_e32 v34, v28, v29
	v_mov_b32_e32 v28, v159
	v_mov_b32_e32 v159, v162
	v_pk_fma_f32 v[30:31], v[36:37], v[30:31], v[32:33]
	v_mov_b32_e32 v29, v163
	v_pk_fma_f32 v[30:31], v[38:39], v[158:159], v[30:31]
	s_nop 0
	v_pk_fma_f32 v[28:29], v[42:43], v[28:29], v[30:31]
	s_nop 0
	v_add_f32_e32 v28, v34, v28
	v_add_f32_e32 v28, v28, v29
	v_mul_f32_e64 v29, |v28|, s31
	v_exp_f32_e32 v29, v29
	v_min_f32_e32 v28, 0, v28
	v_add_f32_e32 v29, 1.0, v29
	v_cmp_gt_f32_e32 vcc, s28, v29
	s_nop 1
	v_cndmask_b32_e64 v30, 0, 32, vcc
	v_ldexp_f32 v29, v29, v30
	v_log_f32_e32 v29, v29
	s_nop 0
	v_mul_f32_e32 v30, 0x3f317217, v29
	v_fma_f32 v30, v29, s29, -v30
	v_fmac_f32_e32 v30, 0x3377d1cf, v29
	v_fmac_f32_e32 v30, 0x3f317217, v29
	v_cmp_lt_f32_e64 s[36:37], |v29|, s30
	s_nop 1
	v_cndmask_b32_e64 v29, v29, v30, s[36:37]
	v_cndmask_b32_e32 v30, 0, v180, vcc
	v_sub_f32_e32 v29, v29, v30
	v_sub_f32_e32 v28, v28, v29
	v_mul_f32_e32 v127, 0x3d800000, v28
.LBB0_878:
	s_or_b64 exec, exec, s[0:1]
	s_waitcnt vmcnt(29)
	v_add_f32_e32 v43, v27, v113
	s_waitcnt vmcnt(28)
	v_add_f32_e32 v41, v43, v116
	v_add_f32_e32 v42, v41, v115
	v_add_f32_e32 v38, v42, v118
	v_add_f32_e32 v39, v38, v117
	v_add_f32_e32 v36, v39, v120
	v_add_f32_e32 v37, v36, v119
	v_add_f32_e32 v34, v37, v122
	v_add_f32_e32 v35, v34, v121
	v_add_f32_e32 v32, v35, v124
	v_add_f32_e32 v33, v32, v123
	v_add_f32_e32 v30, v33, v126
	v_add_f32_e32 v31, v30, v125
	v_add_f32_e32 v28, v31, v128
	v_add_f32_e32 v29, v28, v127
	v_lshl_add_u32 v25, v25, 2, 0
	ds_write_b32 v25, v29 offset:32768
	v_lshl_add_u32 v61, v21, 2, 0
	v_cmp_lt_i32_e32 vcc, 0, v23
	v_mov_b32_e32 v25, 0
	v_mov_b32_e32 v60, 0
	s_waitcnt lgkmcnt(0)
	s_barrier
	s_and_saveexec_b64 s[0:1], vcc
	s_cbranch_execz .LBB0_880
	ds_read_b32 v60, v61 offset:32768
	s_waitcnt lgkmcnt(0)
	v_add_f32_e32 v60, 0, v60
.LBB0_880:
	s_or_b64 exec, exec, s[0:1]
	v_cmp_lt_i32_e32 vcc, 1, v23
	s_and_saveexec_b64 s[0:1], vcc
	ds_read_b32 v25, v61 offset:33024
	s_or_b64 exec, exec, s[0:1]
	v_cmp_lt_i32_e32 vcc, 2, v23
	v_mov_b32_e32 v113, 0
	v_mov_b32_e32 v114, 0
	s_and_saveexec_b64 s[0:1], vcc
	ds_read_b32 v114, v61 offset:33280
	s_or_b64 exec, exec, s[0:1]
	v_cmp_lt_i32_e32 vcc, 3, v23
	s_and_saveexec_b64 s[0:1], vcc
	ds_read_b32 v113, v61 offset:33536
	s_or_b64 exec, exec, s[0:1]
	v_cmp_lt_i32_e32 vcc, 4, v23
	v_mov_b32_e32 v115, 0
	v_mov_b32_e32 v116, 0
	s_and_saveexec_b64 s[0:1], vcc
	ds_read_b32 v116, v61 offset:33792
	s_or_b64 exec, exec, s[0:1]
	v_cmp_lt_i32_e32 vcc, 5, v23
	s_and_saveexec_b64 s[0:1], vcc
	ds_read_b32 v115, v61 offset:34048
	s_or_b64 exec, exec, s[0:1]
	v_cmp_lt_i32_e32 vcc, 6, v23
	v_mov_b32_e32 v117, 0
	v_mov_b32_e32 v118, 0
	s_and_saveexec_b64 s[0:1], vcc
	ds_read_b32 v118, v61 offset:34304
	s_or_b64 exec, exec, s[0:1]
	v_cmp_lt_i32_e32 vcc, 7, v23
	s_and_saveexec_b64 s[0:1], vcc
	ds_read_b32 v117, v61 offset:34560
	s_or_b64 exec, exec, s[0:1]
	s_waitcnt lgkmcnt(0)
	v_add_f32_e32 v25, v60, v25
	v_add_f32_e32 v25, v25, v114
	v_add_f32_e32 v25, v25, v113
	v_add_f32_e32 v25, v25, v116
	v_add_f32_e32 v25, v25, v115
	v_add_f32_e32 v25, v25, v118
	v_add_f32_e32 v25, v25, v117
	v_lshlrev_b32_e32 v23, 12, v23
	v_lshlrev_b32_e32 v21, 2, v21
	v_add3_u32 v21, 0, v23, v21
	v_add_f32_e32 v23, v27, v25
	v_add_f32_e32 v27, v43, v25
	ds_write2st64_b32 v21, v23, v27 offset1:1
	v_add_f32_e32 v23, v41, v25
	v_add_f32_e32 v27, v42, v25
	ds_write2st64_b32 v21, v23, v27 offset0:2 offset1:3
	v_add_f32_e32 v23, v38, v25
	v_add_f32_e32 v27, v39, v25
	ds_write2st64_b32 v21, v23, v27 offset0:4 offset1:5
	v_add_f32_e32 v23, v36, v25
	v_add_f32_e32 v27, v37, v25
	ds_write2st64_b32 v21, v23, v27 offset0:6 offset1:7
	v_add_f32_e32 v23, v34, v25
	v_add_f32_e32 v27, v35, v25
	ds_write2st64_b32 v21, v23, v27 offset0:8 offset1:9
	v_add_f32_e32 v23, v32, v25
	v_add_f32_e32 v27, v33, v25
	ds_write2st64_b32 v21, v23, v27 offset0:10 offset1:11
	v_add_f32_e32 v23, v30, v25
	v_add_f32_e32 v27, v31, v25
	ds_write2st64_b32 v21, v23, v27 offset0:12 offset1:13
	v_add_f32_e32 v23, v28, v25
	v_add_f32_e32 v25, v29, v25
	ds_write2st64_b32 v21, v23, v25 offset0:14 offset1:15
	v_lshl_add_u32 v21, v65, 2, 0
	v_lshl_add_u32 v25, v18, 12, v21
	s_waitcnt lgkmcnt(0)
	s_barrier
	ds_read_b32 v23, v21 offset:16128
	s_waitcnt lgkmcnt(0)
	s_barrier
	s_waitcnt vmcnt(0)
	ds_read_b32 v25, v25
	v_lshlrev_b32_e32 v28, 16, v112
	s_movk_i32 s0, 0x480
	v_lshlrev_b32_e32 v30, 16, v108
	v_lshlrev_b32_e32 v17, 16, v17
	s_waitcnt lgkmcnt(0)
	v_sub_f32_e32 v27, v25, v23
	v_mul_f32_e32 v27, 0x3fb8aa3b, v27
	v_sub_f32_e32 v25, v23, v25
	v_exp_f32_e32 v27, v27
	v_mul_f32_e32 v25, 0x3fb8aa3b, v25
	v_exp_f32_e32 v25, v25
	s_movk_i32 s12, 0x90
	v_mul_f32_e32 v27, v27, v28
	v_lshlrev_b32_e32 v28, 16, v111
	v_mul_f32_e32 v25, v25, v28
	v_mul_lo_u32 v28, v18, s0
	v_or_b32_e32 v28, v28, v65
	v_cvt_pk_bf16_f32 v27, v27, v139
	v_lshl_add_u32 v28, v28, 1, 0
	ds_write_b16 v28, v27 offset:32768
	v_or_b32_e32 v27, 1, v16
	v_lshl_add_u32 v29, v27, 8, v21
	v_cvt_pk_bf16_f32 v25, v25, v139
	ds_read_b32 v29, v29
	ds_write_b16 v28, v25 offset:51200
	s_movk_i32 s0, 0x48
	v_mul_lo_u32 v27, v27, s0
	v_lshl_add_u32 v21, v16, 8, v21
	s_waitcnt lgkmcnt(1)
	v_sub_f32_e32 v25, v29, v23
	v_mul_f32_e32 v25, 0x3fb8aa3b, v25
	v_sub_f32_e32 v28, v23, v29
	v_exp_f32_e32 v25, v25
	v_mul_f32_e32 v28, 0x3fb8aa3b, v28
	v_exp_f32_e32 v28, v28
	v_lshlrev_b32_e32 v29, 16, v110
	v_mul_f32_e32 v25, v25, v29
	v_lshlrev_b32_e32 v29, 16, v109
	v_mul_f32_e32 v28, v28, v29
	v_add_u32_e32 v29, v27, v65
	v_cvt_pk_bf16_f32 v25, v25, v139
	v_lshl_add_u32 v29, v29, 1, 0
	ds_write_b16 v29, v25 offset:32768
	v_cvt_pk_bf16_f32 v25, v28, v139
	ds_read_b32 v28, v21 offset:512
	ds_write_b16 v29, v25 offset:51200
	v_add_u32_e32 v27, 0x1f8, v27
	v_mul_lo_u32 v18, v18, s12
	v_readlane_b32 s13, v249, 31
	s_waitcnt lgkmcnt(1)
	v_sub_f32_e32 v25, v28, v23
	v_mul_f32_e32 v25, 0x3fb8aa3b, v25
	v_sub_f32_e32 v28, v23, v28
	v_exp_f32_e32 v25, v25
	v_mul_f32_e32 v28, 0x3fb8aa3b, v28
	v_exp_f32_e32 v28, v28
	v_add3_u32 v18, s13, v138, v18
	v_mul_f32_e32 v25, v25, v30
	v_lshlrev_b32_e32 v30, 16, v107
	v_mul_f32_e32 v28, v28, v30
	v_cvt_pk_bf16_f32 v25, v25, v139
	ds_write_b16 v29, v25 offset:32912
	v_cvt_pk_bf16_f32 v25, v28, v139
	ds_read_b32 v28, v21 offset:768
	ds_write_b16 v29, v25 offset:51344
	v_lshlrev_b32_e32 v30, 16, v104
	v_readlane_b32 s0, v249, 30
	v_or_b32_e32 v60, v16, v62
	s_waitcnt lgkmcnt(1)
	v_sub_f32_e32 v25, v28, v23
	v_mul_f32_e32 v25, 0x3fb8aa3b, v25
	v_sub_f32_e32 v28, v23, v28
	v_exp_f32_e32 v25, v25
	v_mul_f32_e32 v28, 0x3fb8aa3b, v28
	v_exp_f32_e32 v28, v28
	v_mul_u32_u24_e32 v41, 0x90, v62
	v_mul_f32_e32 v25, v25, v30
	v_lshlrev_b32_e32 v30, 16, v103
	v_mul_f32_e32 v28, v28, v30
	v_cvt_pk_bf16_f32 v25, v25, v139
	ds_write_b16 v29, v25 offset:33056
	v_cvt_pk_bf16_f32 v25, v28, v139
	ds_read_b32 v28, v21 offset:1024
	ds_write_b16 v29, v25 offset:51488
	v_lshlrev_b32_e32 v30, 16, v106
	s_waitcnt lgkmcnt(1)
	v_sub_f32_e32 v25, v28, v23
	v_mul_f32_e32 v25, 0x3fb8aa3b, v25
	v_sub_f32_e32 v28, v23, v28
	v_exp_f32_e32 v25, v25
	v_mul_f32_e32 v28, 0x3fb8aa3b, v28
	v_exp_f32_e32 v28, v28
	v_mul_f32_e32 v25, v25, v30
	v_lshlrev_b32_e32 v30, 16, v105
	v_mul_f32_e32 v28, v28, v30
	v_cvt_pk_bf16_f32 v25, v25, v139
	ds_write_b16 v29, v25 offset:33200
	v_cvt_pk_bf16_f32 v25, v28, v139
	ds_read_b32 v28, v21 offset:1280
	ds_write_b16 v29, v25 offset:51632
	v_lshlrev_b32_e32 v30, 16, v102
	s_waitcnt lgkmcnt(1)
	v_sub_f32_e32 v25, v28, v23
	v_mul_f32_e32 v25, 0x3fb8aa3b, v25
	v_sub_f32_e32 v28, v23, v28
	v_exp_f32_e32 v25, v25
	v_mul_f32_e32 v28, 0x3fb8aa3b, v28
	v_exp_f32_e32 v28, v28
	v_mul_f32_e32 v25, v25, v30
	v_lshlrev_b32_e32 v30, 16, v101
	v_mul_f32_e32 v28, v28, v30
	v_cvt_pk_bf16_f32 v25, v25, v139
	ds_write_b16 v29, v25 offset:33344
	v_cvt_pk_bf16_f32 v25, v28, v139
	ds_read_b32 v28, v21 offset:1536
	ds_write_b16 v29, v25 offset:51776
	v_lshlrev_b32_e32 v30, 16, v100
	s_waitcnt lgkmcnt(1)
	v_sub_f32_e32 v25, v28, v23
	v_mul_f32_e32 v25, 0x3fb8aa3b, v25
	v_sub_f32_e32 v28, v23, v28
	v_exp_f32_e32 v25, v25
	v_mul_f32_e32 v28, 0x3fb8aa3b, v28
	v_exp_f32_e32 v28, v28
	v_mul_f32_e32 v25, v25, v30
	v_lshlrev_b32_e32 v30, 16, v99
	v_mul_f32_e32 v28, v28, v30
	v_cvt_pk_bf16_f32 v25, v25, v139
	ds_write_b16 v29, v25 offset:33488
	v_cvt_pk_bf16_f32 v25, v28, v139
	ds_read_b32 v28, v21 offset:1792
	ds_write_b16 v29, v25 offset:51920
	v_lshlrev_b32_e32 v30, 16, v96
	s_waitcnt lgkmcnt(1)
	v_sub_f32_e32 v25, v28, v23
	v_mul_f32_e32 v25, 0x3fb8aa3b, v25
	v_sub_f32_e32 v28, v23, v28
	v_exp_f32_e32 v25, v25
	v_mul_f32_e32 v28, 0x3fb8aa3b, v28
	v_exp_f32_e32 v28, v28
	v_mul_f32_e32 v25, v25, v30
	v_lshlrev_b32_e32 v30, 16, v95
	v_mul_f32_e32 v28, v28, v30
	v_cvt_pk_bf16_f32 v25, v25, v139
	ds_write_b16 v29, v25 offset:33632
	v_cvt_pk_bf16_f32 v25, v28, v139
	ds_read_b32 v28, v21 offset:2048
	ds_write_b16 v29, v25 offset:52064
	v_lshlrev_b32_e32 v29, 16, v98
	s_waitcnt lgkmcnt(1)
	v_sub_f32_e32 v25, v28, v23
	v_mul_f32_e32 v25, 0x3fb8aa3b, v25
	v_sub_f32_e32 v28, v23, v28
	v_exp_f32_e32 v25, v25
	v_mul_f32_e32 v28, 0x3fb8aa3b, v28
	v_exp_f32_e32 v28, v28
	v_mul_f32_e32 v25, v25, v29
	v_lshlrev_b32_e32 v29, 16, v97
	v_mul_f32_e32 v28, v28, v29
	v_or_b32_e32 v29, v27, v65
	v_cvt_pk_bf16_f32 v25, v25, v139
	v_lshl_add_u32 v29, v29, 1, 0
	ds_write_b16 v29, v25 offset:32768
	v_cvt_pk_bf16_f32 v25, v28, v139
	ds_read_b32 v28, v21 offset:2304
	ds_write_b16 v29, v25 offset:51200
	v_lshlrev_b32_e32 v29, 16, v94
	v_add_u32_e32 v27, v27, v65
	v_lshl_add_u32 v27, v27, 1, 0
	s_waitcnt lgkmcnt(1)
	v_sub_f32_e32 v25, v28, v23
	v_mul_f32_e32 v25, 0x3fb8aa3b, v25
	v_sub_f32_e32 v28, v23, v28
	v_exp_f32_e32 v25, v25
	v_mul_f32_e32 v28, 0x3fb8aa3b, v28
	v_exp_f32_e32 v28, v28
	v_lshlrev_b32_e32 v65, 2, v64
	v_mul_f32_e32 v25, v25, v29
	v_lshlrev_b32_e32 v29, 16, v93
	v_mul_f32_e32 v28, v28, v29
	v_cvt_pk_bf16_f32 v25, v25, v139
	ds_write_b16 v27, v25 offset:32912
	v_cvt_pk_bf16_f32 v25, v28, v139
	ds_read_b32 v28, v21 offset:2560
	ds_write_b16 v27, v25 offset:51344
	v_lshlrev_b32_e32 v29, 16, v89
	s_waitcnt lgkmcnt(1)
	v_sub_f32_e32 v25, v28, v23
	v_mul_f32_e32 v25, 0x3fb8aa3b, v25
	v_sub_f32_e32 v28, v23, v28
	v_exp_f32_e32 v25, v25
	v_mul_f32_e32 v28, 0x3fb8aa3b, v28
	v_exp_f32_e32 v28, v28
	v_mul_f32_e32 v25, v25, v29
	v_lshlrev_b32_e32 v29, 16, v88
	v_mul_f32_e32 v28, v28, v29
	v_cvt_pk_bf16_f32 v25, v25, v139
	ds_write_b16 v27, v25 offset:33056
	v_cvt_pk_bf16_f32 v25, v28, v139
	ds_read_b32 v28, v21 offset:2816
	ds_write_b16 v27, v25 offset:51488
	v_lshlrev_b32_e32 v29, 16, v77
	s_waitcnt lgkmcnt(1)
	v_sub_f32_e32 v25, v28, v23
	v_mul_f32_e32 v25, 0x3fb8aa3b, v25
	v_sub_f32_e32 v28, v23, v28
	v_exp_f32_e32 v25, v25
	v_mul_f32_e32 v28, 0x3fb8aa3b, v28
	v_exp_f32_e32 v28, v28
	v_mul_f32_e32 v25, v25, v29
	v_lshlrev_b32_e32 v29, 16, v76
	v_mul_f32_e32 v28, v28, v29
	v_cvt_pk_bf16_f32 v25, v25, v139
	ds_write_b16 v27, v25 offset:33200
	v_cvt_pk_bf16_f32 v25, v28, v139
	ds_read_b32 v28, v21 offset:3072
	ds_write_b16 v27, v25 offset:51632
	v_lshlrev_b32_e32 v29, 16, v83
	s_waitcnt lgkmcnt(1)
	v_sub_f32_e32 v25, v28, v23
	v_mul_f32_e32 v25, 0x3fb8aa3b, v25
	v_sub_f32_e32 v28, v23, v28
	v_exp_f32_e32 v25, v25
	v_mul_f32_e32 v28, 0x3fb8aa3b, v28
	v_exp_f32_e32 v28, v28
	v_mul_f32_e32 v25, v25, v29
	v_lshlrev_b32_e32 v29, 16, v81
	v_mul_f32_e32 v28, v28, v29
	v_cvt_pk_bf16_f32 v25, v25, v139
	ds_write_b16 v27, v25 offset:33344
	v_cvt_pk_bf16_f32 v25, v28, v139
	ds_read_b32 v28, v21 offset:3328
	ds_write_b16 v27, v25 offset:51776
	v_lshlrev_b32_e32 v29, 16, v75
	s_waitcnt lgkmcnt(1)
	v_sub_f32_e32 v25, v28, v23
	v_mul_f32_e32 v25, 0x3fb8aa3b, v25
	v_sub_f32_e32 v28, v23, v28
	v_exp_f32_e32 v25, v25
	v_mul_f32_e32 v28, 0x3fb8aa3b, v28
	v_exp_f32_e32 v28, v28
	v_mul_f32_e32 v25, v25, v29
	v_lshlrev_b32_e32 v29, 16, v74
	v_mul_f32_e32 v28, v28, v29
	v_cvt_pk_bf16_f32 v25, v25, v139
	ds_write_b16 v27, v25 offset:33488
	v_cvt_pk_bf16_f32 v25, v28, v139
	ds_read_b32 v28, v21 offset:3584
	ds_write_b16 v27, v25 offset:51920
	v_lshlrev_b32_e32 v29, 16, v68
	s_waitcnt lgkmcnt(1)
	v_sub_f32_e32 v25, v28, v23
	v_mul_f32_e32 v25, 0x3fb8aa3b, v25
	v_exp_f32_e32 v25, v25
	v_sub_f32_e32 v28, v23, v28
	v_mul_f32_e32 v28, 0x3fb8aa3b, v28
	v_exp_f32_e32 v28, v28
	v_mul_f32_e32 v25, v25, v29
	v_lshlrev_b32_e32 v29, 16, v67
	v_cvt_pk_bf16_f32 v25, v25, v139
	v_mul_f32_e32 v28, v28, v29
	ds_write_b16 v27, v25 offset:33632
	v_cvt_pk_bf16_f32 v25, v28, v139
	ds_read_b32 v21, v21 offset:3840
	ds_write_b16 v27, v25 offset:52064
	v_lshlrev_b32_e32 v28, 16, v66
	s_waitcnt lgkmcnt(1)
	v_sub_f32_e32 v25, v21, v23
	v_sub_f32_e32 v21, v23, v21
	v_mul_f32_e32 v21, 0x3fb8aa3b, v21
	v_mul_f32_e32 v25, 0x3fb8aa3b, v25
	v_exp_f32_e32 v21, v21
	v_exp_f32_e32 v25, v25
	v_mul_f32_e32 v23, 0x3fb8aa3b, v23
	v_exp_f32_e32 v23, v23
	v_mul_f32_e32 v17, v21, v17
	v_mul_f32_e32 v25, v25, v28
	v_cvt_pk_bf16_f32 v21, v25, v139
	ds_write_b16 v27, v21 offset:33776
	v_cvt_pk_bf16_f32 v17, v17, v139
	ds_write_b16 v27, v17 offset:52208
	v_mul_f32_e32 v17, v73, v23
	v_cvt_pk_bf16_f32 v17, v17, v139
	ds_write_b16 v18, v17
	v_mul_f32_e32 v17, v69, v23
	v_cvt_pk_bf16_f32 v17, v17, v139
	ds_write_b16 v18, v17 offset:1152
	v_mul_f32_e32 v17, v72, v23
	v_cvt_pk_bf16_f32 v17, v17, v139
	ds_write_b16 v18, v17 offset:2304
	v_mul_f32_e32 v17, v71, v23
	v_cvt_pk_bf16_f32 v17, v17, v139
	ds_write_b16 v18, v17 offset:3456
	v_mul_f32_e32 v17, v70, v23
	v_cvt_pk_bf16_f32 v17, v17, v139
	ds_write_b16 v18, v17 offset:4608
	v_mul_f32_e32 v17, v19, v23
	v_cvt_pk_bf16_f32 v17, v17, v139
	ds_write_b16 v18, v17 offset:5760
	v_mul_f32_e32 v17, v82, v23
	v_cvt_pk_bf16_f32 v17, v17, v139
	ds_write_b16 v18, v17 offset:6912
	v_mul_f32_e32 v17, v79, v23
	v_cvt_pk_bf16_f32 v17, v17, v139
	ds_write_b16 v18, v17 offset:8064
	v_mul_f32_e32 v17, v80, v23
	v_cvt_pk_bf16_f32 v17, v17, v139
	ds_write_b16 v18, v17 offset:9216
	v_mul_f32_e32 v17, v78, v23
	v_cvt_pk_bf16_f32 v17, v17, v139
	ds_write_b16 v18, v17 offset:10368
	v_mul_f32_e32 v17, v87, v23
	v_cvt_pk_bf16_f32 v17, v17, v139
	ds_write_b16 v18, v17 offset:11520
	v_mul_f32_e32 v17, v85, v23
	v_cvt_pk_bf16_f32 v17, v17, v139
	ds_write_b16 v18, v17 offset:12672
	v_mul_f32_e32 v17, v86, v23
	v_cvt_pk_bf16_f32 v17, v17, v139
	ds_write_b16 v18, v17 offset:13824
	v_mul_f32_e32 v17, v84, v23
	v_cvt_pk_bf16_f32 v17, v17, v139
	ds_write_b16 v18, v17 offset:14976
	v_mul_f32_e32 v17, v92, v23
	v_cvt_pk_bf16_f32 v17, v17, v139
	ds_write_b16 v18, v17 offset:16128
	v_mul_f32_e32 v17, v91, v23
	v_cvt_pk_bf16_f32 v17, v17, v139
	ds_write_b16 v18, v17 offset:17280
	v_lshl_add_u32 v18, v90, 1, s0
	v_mad_u64_u32 v[20:21], s[0:1], v20, s10, v[18:19]
	ds_write_b16 v20, v0
	ds_write_b16_d16_hi v20, v0 offset:272
	ds_write_b16 v20, v1 offset:544
	ds_write_b16_d16_hi v20, v1 offset:816
	ds_write_b16 v20, v2 offset:1088
	ds_write_b16_d16_hi v20, v2 offset:1360
	ds_write_b16 v20, v3 offset:1632
	ds_write_b16_d16_hi v20, v3 offset:1904
	v_mad_u64_u32 v[0:1], s[0:1], v22, s10, v[18:19]
	ds_write_b16 v0, v8
	ds_write_b16_d16_hi v0, v8 offset:272
	ds_write_b16 v0, v9 offset:544
	ds_write_b16_d16_hi v0, v9 offset:816
	ds_write_b16 v0, v10 offset:1088
	ds_write_b16_d16_hi v0, v10 offset:1360
	ds_write_b16 v0, v11 offset:1632
	ds_write_b16_d16_hi v0, v11 offset:1904
	v_mad_u64_u32 v[0:1], s[0:1], v24, s10, v[18:19]
	ds_write_b16 v0, v4
	ds_write_b16_d16_hi v0, v4 offset:272
	ds_write_b16 v0, v5 offset:544
	ds_write_b16_d16_hi v0, v5 offset:816
	ds_write_b16 v0, v6 offset:1088
	ds_write_b16_d16_hi v0, v6 offset:1360
	ds_write_b16 v0, v7 offset:1632
	ds_write_b16_d16_hi v0, v7 offset:1904
	v_and_b32_e32 v4, 48, v63
	v_mul_lo_u32 v5, v60, s12
	v_mad_u64_u32 v[0:1], s[0:1], v26, s10, v[18:19]
	v_add3_u32 v42, s13, v4, v41
	v_add3_u32 v24, 0, v5, v4
	ds_write_b16 v0, v12
	ds_write_b16_d16_hi v0, v12 offset:272
	ds_write_b16 v0, v13 offset:544
	ds_write_b16_d16_hi v0, v13 offset:816
	ds_write_b16 v0, v14 offset:1088
	ds_write_b16_d16_hi v0, v14 offset:1360
	ds_write_b16 v0, v15 offset:1632
	ds_write_b16_d16_hi v0, v15 offset:1904
	s_waitcnt lgkmcnt(0)
	s_barrier
	ds_read_b128 v[0:3], v42
	ds_read_b128 v[32:35], v24 offset:32768
	ds_read_b128 v[4:7], v42 offset:2304
	ds_read_b128 v[16:19], v42 offset:9216
	ds_read_b128 v[20:23], v42 offset:11520
	s_waitcnt lgkmcnt(1)
	v_mfma_f32_16x16x32_bf16 v[66:69], v[16:19], v[32:35], 0
	ds_read_b128 v[16:19], v42 offset:13824
	ds_read_b128 v[36:39], v24 offset:32832
	ds_read_b128 v[8:11], v42 offset:4608
	s_waitcnt lgkmcnt(3)
	v_mfma_f32_16x16x32_bf16 v[70:73], v[20:23], v[32:35], 0
	ds_read_b128 v[20:23], v42 offset:16128
	ds_read_b128 v[12:15], v42 offset:6912
	s_waitcnt lgkmcnt(4)
	v_mfma_f32_16x16x32_bf16 v[74:77], v[16:19], v[32:35], 0
	ds_read_b128 v[16:19], v42 offset:64
	v_mfma_f32_16x16x32_bf16 v[0:3], v[0:3], v[32:35], 0
	s_waitcnt lgkmcnt(0)
	v_mfma_f32_16x16x32_bf16 v[28:31], v[16:19], v[36:39], v[0:3]
	s_nop 5
	ds_read_b128 v[0:3], v42 offset:2368
	v_mfma_f32_16x16x32_bf16 v[4:7], v[4:7], v[32:35], 0
	s_waitcnt lgkmcnt(0)
	v_mfma_f32_16x16x32_bf16 v[24:27], v[0:3], v[36:39], v[4:7]
	ds_read_b128 v[0:3], v42 offset:4672
	v_mfma_f32_16x16x32_bf16 v[8:11], v[8:11], v[32:35], 0
	v_mfma_f32_16x16x32_bf16 v[78:81], v[20:23], v[32:35], 0
	s_waitcnt lgkmcnt(0)
	v_mfma_f32_16x16x32_bf16 v[20:23], v[0:3], v[36:39], v[8:11]
	ds_read_b128 v[0:3], v42 offset:6976
	v_mfma_f32_16x16x32_bf16 v[12:15], v[12:15], v[32:35], 0
	s_waitcnt lgkmcnt(0)
	v_mfma_f32_16x16x32_bf16 v[16:19], v[0:3], v[36:39], v[12:15]
	ds_read_b128 v[0:3], v42 offset:9280
	s_waitcnt lgkmcnt(0)
	v_mfma_f32_16x16x32_bf16 v[12:15], v[0:3], v[36:39], v[66:69]
	ds_read_b128 v[0:3], v42 offset:11584
	s_waitcnt lgkmcnt(0)
	v_mfma_f32_16x16x32_bf16 v[8:11], v[0:3], v[36:39], v[70:73]
	ds_read_b128 v[0:3], v42 offset:13888
	s_waitcnt lgkmcnt(0)
	v_mfma_f32_16x16x32_bf16 v[4:7], v[0:3], v[36:39], v[74:77]
	ds_read_b128 v[0:3], v42 offset:16192
	v_ashrrev_i32_e32 v42, 7, v63
	v_cmp_lt_i32_e32 vcc, -1, v42
	s_waitcnt lgkmcnt(0)
	v_mfma_f32_16x16x32_bf16 v[0:3], v[0:3], v[36:39], v[78:81]
	s_and_saveexec_b64 s[12:13], vcc
	s_cbranch_execz .LBB0_845
	v_mad_u32_u24 v62, v62, s10, v40
	v_lshlrev_b32_e32 v40, 4, v64
	s_mov_b32 s0, 0xc800
	v_add_u32_e32 v61, 1, v42
	v_add_u32_e32 v63, 19, v65
	v_add3_u32 v64, v41, v40, s0
	s_mov_b64 s[0:1], 0
